# speedup vs baseline: 1.0171x; 1.0059x over previous
;     __device__ __forceinline__ float* out() const { return (float*)(__attribute__((address_space(1))) float*)ka[32]; }
; __device__ __forceinline__ unsigned cvtpk(float lo, float hi) { unsigned r; asm("v_cvt_pk_bf16_f32 %0, %1, %2" : "=v"(r) : "v"(lo), "v"(hi)); return r; }
; __device__ __forceinline__ float bf1(bf16_t h) { return __uint_as_float((unsigned)h << 16); }
; __device__ __forceinline__ float gelu_t(float x) { const float u = 0.7978845608f * (x + 0.044715f * x * x * x); return x * sigm(2.f * u); }
; __device__ __forceinline__ float wave_sum(float v) {
; #pragma unroll
;     for (int o = 1; o < 64; o <<= 1) v += __shfl_xor(v, o);
;     return v;
; }
; __device__ __forceinline__ void phase_branch(const KP2& p, int l, LAS unsigned char* lds) {
;     ...
;             for (int ib = wave; ib < R; ib += 32) {
;                 float vv[4][4];
; #pragma unroll
;                 for (int r4 = 0; r4 < 4; ++r4) { const int i = ib + 8 * r4; const bf16_t* zr = Z + (size_t)(row0 + (i < R ? i : 0)) * ZP + 256;
; #pragma unroll
;                     for (int k = 0; k < 4; ++k) vv[r4][k] = bf1(zr[lane + 64 * k]); }
; #pragma unroll
;                 for (int r4 = 0; r4 < 4; ++r4) { const int i = ib + 8 * r4; if (i < R) {
;                     float v[4]; float s = 0.f;
; #pragma unroll
;                     for (int k = 0; k < 4; ++k) { v[k] = gelu_t(vv[r4][k]); s += v[k]; }
;                     const float mu = wave_sum(s) * (1.f / BW); float q = 0.f;
; #pragma unroll
;                     for (int k = 0; k < 4; ++k) { v[k] -= mu; q += v[k] * v[k]; }
;                     const float rs = rsqrtf(wave_sum(q) * (1.f / BW) + EPS);
; #pragma unroll
;                     for (int k = 0; k < 4; ++k) { const float y = v[k] * rs * gk[k] + bk[k]; vT[(lane + 64 * k) * 136 + i] = (bf16_t)(cvtpk(y, 0.f) & 0xffffu);
;                         if (smp) out[O_AVS + ((size_t)(l * NBS + b) * SSEQ + i) * BW + lane + 64 * k] = y; }
;                 } }
.LBB0_378:
	v_add_u32_e32 v2, 8, v23
	v_cmp_gt_i32_e64 s[14:15], s54, v2
	s_nop 1
	v_cndmask_b32_e64 v2, 0, v2, s[14:15]
	v_add_u32_e32 v2, s5, v2
	v_mad_i64_i32 v[2:3], s[10:11], v2, s83, v[134:135]
	global_load_ushort v35, v[2:3], off offset:512
	global_load_ushort v32, v[2:3], off offset:640
	global_load_ushort v33, v[2:3], off offset:768
	global_load_ushort v34, v[2:3], off offset:896
	v_add_u32_e32 v2, 16, v23
	v_cmp_gt_i32_e64 s[12:13], s54, v2
	s_nop 1
	v_cndmask_b32_e64 v2, 0, v2, s[12:13]
	v_add_u32_e32 v2, s5, v2
	v_mad_i64_i32 v[2:3], s[10:11], v2, s83, v[134:135]
	global_load_ushort v31, v[2:3], off offset:512
	global_load_ushort v28, v[2:3], off offset:640
	global_load_ushort v29, v[2:3], off offset:768
	global_load_ushort v30, v[2:3], off offset:896
	v_add_u32_e32 v2, 24, v23
	v_cmp_gt_i32_e64 s[10:11], s54, v2
	s_nop 1
	v_cndmask_b32_e64 v2, 0, v2, s[10:11]
	v_add_u32_e32 v2, s5, v2
	v_mad_i64_i32 v[2:3], s[16:17], v2, s83, v[134:135]
	global_load_ushort v27, v[2:3], off offset:512
	global_load_ushort v24, v[2:3], off offset:640
	global_load_ushort v25, v[2:3], off offset:768
	global_load_ushort v26, v[2:3], off offset:896
	v_add_u32_e32 v2, s5, v23
	v_mad_i64_i32 v[36:37], s[16:17], v2, s83, v[134:135]
	global_load_ushort v2, v[36:37], off offset:896
	global_load_ushort v3, v[36:37], off offset:768
	global_load_ushort v38, v[36:37], off offset:512
	s_nop 0
	global_load_ushort v36, v[36:37], off offset:640
	s_waitcnt vmcnt(3)
	v_lshlrev_b32_e32 v2, 16, v2
	s_waitcnt vmcnt(2)
	v_lshlrev_b32_e32 v3, 16, v3
	v_mul_f32_e32 v4, 0x3d372713, v3
	v_mul_f32_e32 v4, v4, v3
	v_mov_b32_e32 v5, v3
	v_fmac_f32_e32 v5, v4, v5
	v_mul_f32_e32 v4, 0x3f4c422a, v5
	v_add_f32_e32 v4, v4, v4
	v_mul_f32_e32 v4, 0xbfb8aa3b, v4
	s_waitcnt vmcnt(0)
	v_lshlrev_b32_e32 v37, 16, v36
	v_lshlrev_b32_e32 v36, 16, v38
	v_exp_f32_e32 v4, v4
	v_mul_f32_e32 v38, 0x3d372713, v36
	v_mul_f32_e32 v38, v38, v36
	v_mov_b32_e32 v39, v36
	v_fmac_f32_e32 v39, v38, v39
	v_mul_f32_e32 v38, 0x3f4c422a, v39
	v_mul_f32_e32 v39, 0x3d372713, v37
	v_add_f32_e32 v4, 1.0, v4
	v_mul_f32_e32 v39, v39, v37
	v_mov_b32_e32 v40, v37
	v_rcp_f32_e32 v5, v4
	v_mul_f32_e32 v4, 0x3d372713, v2
	v_fmac_f32_e32 v40, v39, v40
	v_mul_f32_e32 v4, v4, v2
	v_mov_b32_e32 v6, v2
	v_mul_f32_e32 v39, 0x3f4c422a, v40
	v_fmac_f32_e32 v6, v4, v6
	v_add_f32_e32 v38, v38, v38
	v_add_f32_e32 v39, v39, v39
	v_mul_f32_e32 v4, 0x3f4c422a, v6
	v_mul_f32_e32 v38, 0xbfb8aa3b, v38
	v_mul_f32_e32 v39, 0xbfb8aa3b, v39
	v_add_f32_e32 v4, v4, v4
	v_exp_f32_e32 v38, v38
	v_exp_f32_e32 v39, v39
	v_mul_f32_e32 v4, 0xbfb8aa3b, v4
	v_exp_f32_e32 v4, v4
	v_add_f32_e32 v38, 1.0, v38
	v_add_f32_e32 v39, 1.0, v39
	v_rcp_f32_e32 v38, v38
	v_rcp_f32_e32 v39, v39
	v_add_f32_e32 v4, 1.0, v4
	v_rcp_f32_e32 v4, v4
	v_pk_mul_f32 v[40:41], v[38:39], v[36:37]
	s_nop 0
	v_add_f32_e32 v40, 0, v40
	v_pk_mul_f32 v[6:7], v[4:5], v[2:3]
	v_add_f32_e32 v40, v41, v40
	v_add_f32_e32 v7, v7, v40
	v_add_f32_e32 v6, v6, v7
	s_nop 1
	v_add_f32_dpp v6, v6, v6 quad_perm:[1,0,3,2] row_mask:0xf bank_mask:0xf
	s_nop 1
	v_add_f32_dpp v6, v6, v6 quad_perm:[2,3,0,1] row_mask:0xf bank_mask:0xf
	s_nop 1
	v_add_f32_dpp v6, v6, v6 row_half_mirror row_mask:0xf bank_mask:0xf
	s_nop 1
	v_add_f32_dpp v6, v6, v6 row_mirror row_mask:0xf bank_mask:0xf
	ds_bpermute_b32 v7, v20, v6
	s_waitcnt lgkmcnt(0)
	v_add_f32_e32 v6, v6, v7
	ds_bpermute_b32 v7, v21, v6
	s_waitcnt lgkmcnt(0)
	v_add_f32_e32 v6, v6, v7
	v_mul_f32_e32 v40, 0x3b800000, v6
	v_pk_fma_f32 v[6:7], v[38:39], v[36:37], v[40:41] op_sel_hi:[1,1,0] neg_lo:[0,0,1] neg_hi:[0,0,1]
	v_pk_fma_f32 v[2:3], v[4:5], v[2:3], v[40:41] op_sel_hi:[1,1,0] neg_lo:[0,0,1] neg_hi:[0,0,1]
	v_pk_mul_f32 v[36:37], v[6:7], v[6:7]
	v_pk_mul_f32 v[4:5], v[2:3], v[2:3]
	v_add_f32_e32 v36, v36, v37
	v_add_f32_e32 v5, v5, v36
	v_add_f32_e32 v4, v4, v5
	s_nop 1
	v_add_f32_dpp v4, v4, v4 quad_perm:[1,0,3,2] row_mask:0xf bank_mask:0xf
	s_nop 1
	v_add_f32_dpp v4, v4, v4 quad_perm:[2,3,0,1] row_mask:0xf bank_mask:0xf
	s_nop 1
	v_add_f32_dpp v4, v4, v4 row_half_mirror row_mask:0xf bank_mask:0xf
	s_nop 1
	v_add_f32_dpp v4, v4, v4 row_mirror row_mask:0xf bank_mask:0xf
	ds_bpermute_b32 v5, v20, v4
	s_waitcnt lgkmcnt(0)
	v_add_f32_e32 v4, v4, v5
	ds_bpermute_b32 v5, v21, v4
	s_waitcnt lgkmcnt(0)
	v_add_f32_e32 v4, v4, v5
	v_fmamk_f32 v4, v4, 0x3b800000, v196
	v_cmp_gt_f32_e32 vcc, s92, v4
	v_mul_f32_e32 v5, 0x4b800000, v4
	s_nop 0
	v_cndmask_b32_e32 v4, v4, v5, vcc
	v_rsq_f32_e32 v4, v4
	s_nop 0
	v_mul_f32_e32 v5, 0x45800000, v4
	v_cndmask_b32_e32 v4, v4, v5, vcc
	v_mul_f32_e32 v5, v6, v4
	v_fma_f32 v5, v8, v5, v10
	v_cvt_pk_bf16_f32 v6, v5, v145
	ds_write_b16 v22, v6
	v_cndmask_b32_e64 v6, 0, 1, s[22:23]
	v_cmp_ne_u32_e64 s[16:17], 1, v6
	s_andn2_b64 vcc, exec, s[22:23]
	s_cbranch_vccnz .LBB0_380
	global_store_dword v[0:1], v5, off

;     __device__ __forceinline__ float* out() const { return (float*)(__attribute__((address_space(1))) float*)ka[32]; }
; __device__ __forceinline__ unsigned cvtpk(float lo, float hi) { unsigned r; asm("v_cvt_pk_bf16_f32 %0, %1, %2" : "=v"(r) : "v"(lo), "v"(hi)); return r; }
; __device__ __forceinline__ float gelu_t(float x) { const float u = 0.7978845608f * (x + 0.044715f * x * x * x); return x * sigm(2.f * u); }
; __device__ __forceinline__ float wave_sum(float v) {
; #pragma unroll
;     for (int o = 1; o < 64; o <<= 1) v += __shfl_xor(v, o);
;     return v;
; }
; __device__ __forceinline__ void phase_branch(const KP2& p, int l, LAS unsigned char* lds) {
;     ...
;                 for (int r4 = 0; r4 < 4; ++r4) { const int i = ib + 8 * r4; if (i < R) {
;                     float v[4]; float s = 0.f;
; #pragma unroll
;                     for (int k = 0; k < 4; ++k) { v[k] = gelu_t(vv[r4][k]); s += v[k]; }
;                     const float mu = wave_sum(s) * (1.f / BW); float q = 0.f;
; #pragma unroll
;                     for (int k = 0; k < 4; ++k) { v[k] -= mu; q += v[k] * v[k]; }
;                     const float rs = rsqrtf(wave_sum(q) * (1.f / BW) + EPS);
; #pragma unroll
;                     for (int k = 0; k < 4; ++k) { const float y = v[k] * rs * gk[k] + bk[k]; vT[(lane + 64 * k) * 136 + i] = (bf16_t)(cvtpk(y, 0.f) & 0xffffu);
;                         if (smp) out[O_AVS + ((size_t)(l * NBS + b) * SSEQ + i) * BW + lane + 64 * k] = y; }
.LBB0_386:
	s_and_saveexec_b64 s[48:49], s[14:15]
	s_cbranch_execz .LBB0_395
	v_lshlrev_b32_e32 v2, 16, v35
	v_mul_f32_e32 v3, 0x3d372713, v2
	v_mul_f32_e32 v3, v3, v2
	v_mov_b32_e32 v4, v2
	v_fmac_f32_e32 v4, v3, v4
	v_mul_f32_e32 v3, 0x3f4c422a, v4
	v_add_f32_e32 v3, v3, v3
	v_mul_f32_e32 v3, 0xbfb8aa3b, v3
	v_exp_f32_e32 v4, v3
	v_lshlrev_b32_e32 v3, 16, v32
	v_mul_f32_e32 v5, 0x3d372713, v3
	v_mul_f32_e32 v5, v5, v3
	v_mov_b32_e32 v32, v3
	v_lshlrev_b32_e32 v7, 16, v33
	v_fmac_f32_e32 v32, v5, v32
	v_mul_f32_e32 v5, 0x3f4c422a, v32
	v_mul_f32_e32 v32, 0x3d372713, v7
	v_mul_f32_e32 v32, v32, v7
	v_mov_b32_e32 v33, v7
	v_lshlrev_b32_e32 v6, 16, v34
	v_fmac_f32_e32 v33, v32, v33
	v_mul_f32_e32 v32, 0x3f4c422a, v33
	v_mul_f32_e32 v33, 0x3d372713, v6
	v_mul_f32_e32 v33, v33, v6
	v_mov_b32_e32 v34, v6
	v_add_f32_e32 v5, v5, v5
	v_fmac_f32_e32 v34, v33, v34
	v_mul_f32_e32 v5, 0xbfb8aa3b, v5
	v_add_f32_e32 v32, v32, v32
	v_mul_f32_e32 v33, 0x3f4c422a, v34
	v_exp_f32_e32 v5, v5
	v_mul_f32_e32 v32, 0xbfb8aa3b, v32
	v_add_f32_e32 v33, v33, v33
	v_exp_f32_e32 v32, v32
	v_mul_f32_e32 v33, 0xbfb8aa3b, v33
	v_exp_f32_e32 v34, v33
	v_add_f32_e32 v4, 1.0, v4
	v_add_f32_e32 v5, 1.0, v5
	v_rcp_f32_e32 v4, v4
	v_add_f32_e32 v32, 1.0, v32
	v_rcp_f32_e32 v5, v5
	v_rcp_f32_e32 v33, v32
	v_add_f32_e32 v32, 1.0, v34
	v_rcp_f32_e32 v32, v32
	v_pk_mul_f32 v[36:37], v[4:5], v[2:3]
	v_pk_mul_f32 v[34:35], v[32:33], v[6:7]
	v_add_f32_e32 v36, 0, v36
	v_add_f32_e32 v36, v36, v37
	v_add_f32_e32 v35, v36, v35
	v_add_f32_e32 v34, v35, v34
	s_nop 1
	v_add_f32_dpp v34, v34, v34 quad_perm:[1,0,3,2] row_mask:0xf bank_mask:0xf
	s_nop 1
	v_add_f32_dpp v34, v34, v34 quad_perm:[2,3,0,1] row_mask:0xf bank_mask:0xf
	s_nop 1
	v_add_f32_dpp v34, v34, v34 row_half_mirror row_mask:0xf bank_mask:0xf
	s_nop 1
	v_add_f32_dpp v34, v34, v34 row_mirror row_mask:0xf bank_mask:0xf
	ds_bpermute_b32 v35, v20, v34
	s_waitcnt lgkmcnt(0)
	v_add_f32_e32 v34, v34, v35
	ds_bpermute_b32 v35, v21, v34
	s_waitcnt lgkmcnt(0)
	v_add_f32_e32 v34, v34, v35
	v_mul_f32_e32 v34, 0x3b800000, v34
	v_pk_fma_f32 v[4:5], v[4:5], v[2:3], v[34:35] op_sel_hi:[1,1,0] neg_lo:[0,0,1] neg_hi:[0,0,1]
	v_pk_fma_f32 v[2:3], v[32:33], v[6:7], v[34:35] op_sel_hi:[1,1,0] neg_lo:[0,0,1] neg_hi:[0,0,1]
	v_pk_mul_f32 v[36:37], v[4:5], v[4:5]
	v_pk_mul_f32 v[6:7], v[2:3], v[2:3]
	v_add_f32_e32 v32, v36, v37
	v_add_f32_e32 v7, v7, v32
	v_add_f32_e32 v6, v6, v7
	s_nop 1
	v_add_f32_dpp v6, v6, v6 quad_perm:[1,0,3,2] row_mask:0xf bank_mask:0xf
	s_nop 1
	v_add_f32_dpp v6, v6, v6 quad_perm:[2,3,0,1] row_mask:0xf bank_mask:0xf
	s_nop 1
	v_add_f32_dpp v6, v6, v6 row_half_mirror row_mask:0xf bank_mask:0xf
	s_nop 1
	v_add_f32_dpp v6, v6, v6 row_mirror row_mask:0xf bank_mask:0xf
	ds_bpermute_b32 v7, v20, v6
	s_waitcnt lgkmcnt(0)
	v_add_f32_e32 v6, v6, v7
	ds_bpermute_b32 v7, v21, v6
	s_waitcnt lgkmcnt(0)
	v_add_f32_e32 v6, v6, v7
	v_fmamk_f32 v6, v6, 0x3b800000, v196
	v_mul_f32_e32 v7, 0x4b800000, v6
	v_cmp_gt_f32_e32 vcc, s92, v6
	s_nop 1
	v_cndmask_b32_e32 v6, v6, v7, vcc
	v_rsq_f32_e32 v6, v6
	s_nop 0
	v_mul_f32_e32 v7, 0x45800000, v6
	v_cndmask_b32_e32 v6, v6, v7, vcc
	v_mul_f32_e32 v4, v4, v6
	v_fma_f32 v4, v8, v4, v10
	s_and_b64 vcc, exec, s[16:17]
	v_cvt_pk_bf16_f32 v7, v4, v145
	ds_write_b16 v22, v7 offset:16
	s_cbranch_vccnz .LBB0_389
	v_add_co_u32_e32 v32, vcc, 0x2000, v0
	s_nop 1
	v_addc_co_u32_e32 v33, vcc, 0, v1, vcc
	global_store_dword v[32:33], v4, off

;     __device__ __forceinline__ float* out() const { return (float*)(__attribute__((address_space(1))) float*)ka[32]; }
; __device__ __forceinline__ unsigned cvtpk(float lo, float hi) { unsigned r; asm("v_cvt_pk_bf16_f32 %0, %1, %2" : "=v"(r) : "v"(lo), "v"(hi)); return r; }
; __device__ __forceinline__ float gelu_t(float x) { const float u = 0.7978845608f * (x + 0.044715f * x * x * x); return x * sigm(2.f * u); }
; __device__ __forceinline__ float wave_sum(float v) {
; #pragma unroll
;     for (int o = 1; o < 64; o <<= 1) v += __shfl_xor(v, o);
;     return v;
; }
; __device__ __forceinline__ void phase_branch(const KP2& p, int l, LAS unsigned char* lds) {
;     ...
;                 for (int r4 = 0; r4 < 4; ++r4) { const int i = ib + 8 * r4; if (i < R) {
;                     float v[4]; float s = 0.f;
; #pragma unroll
;                     for (int k = 0; k < 4; ++k) { v[k] = gelu_t(vv[r4][k]); s += v[k]; }
;                     const float mu = wave_sum(s) * (1.f / BW); float q = 0.f;
; #pragma unroll
;                     for (int k = 0; k < 4; ++k) { v[k] -= mu; q += v[k] * v[k]; }
;                     const float rs = rsqrtf(wave_sum(q) * (1.f / BW) + EPS);
; #pragma unroll
;                     for (int k = 0; k < 4; ++k) { const float y = v[k] * rs * gk[k] + bk[k]; vT[(lane + 64 * k) * 136 + i] = (bf16_t)(cvtpk(y, 0.f) & 0xffffu);
;                         if (smp) out[O_AVS + ((size_t)(l * NBS + b) * SSEQ + i) * BW + lane + 64 * k] = y; }
.LBB0_395:
	s_or_b64 exec, exec, s[48:49]
	s_and_saveexec_b64 s[14:15], s[12:13]
	s_cbranch_execz .LBB0_404
	v_lshlrev_b32_e32 v2, 16, v31
	v_mul_f32_e32 v3, 0x3d372713, v2
	v_mul_f32_e32 v3, v3, v2
	v_mov_b32_e32 v4, v2
	v_fmac_f32_e32 v4, v3, v4
	v_mul_f32_e32 v3, 0x3f4c422a, v4
	v_add_f32_e32 v3, v3, v3
	v_mul_f32_e32 v3, 0xbfb8aa3b, v3
	v_exp_f32_e32 v4, v3
	v_lshlrev_b32_e32 v3, 16, v28
	v_mul_f32_e32 v5, 0x3d372713, v3
	v_mul_f32_e32 v5, v5, v3
	v_mov_b32_e32 v28, v3
	v_lshlrev_b32_e32 v7, 16, v29
	v_fmac_f32_e32 v28, v5, v28
	v_mul_f32_e32 v5, 0x3f4c422a, v28
	v_mul_f32_e32 v28, 0x3d372713, v7
	v_mul_f32_e32 v28, v28, v7
	v_mov_b32_e32 v29, v7
	v_lshlrev_b32_e32 v6, 16, v30
	v_fmac_f32_e32 v29, v28, v29
	v_mul_f32_e32 v28, 0x3f4c422a, v29
	v_mul_f32_e32 v29, 0x3d372713, v6
	v_mul_f32_e32 v29, v29, v6
	v_mov_b32_e32 v30, v6
	v_add_f32_e32 v5, v5, v5
	v_fmac_f32_e32 v30, v29, v30
	v_mul_f32_e32 v5, 0xbfb8aa3b, v5
	v_add_f32_e32 v28, v28, v28
	v_mul_f32_e32 v29, 0x3f4c422a, v30
	v_exp_f32_e32 v5, v5
	v_mul_f32_e32 v28, 0xbfb8aa3b, v28
	v_add_f32_e32 v29, v29, v29
	v_exp_f32_e32 v28, v28
	v_mul_f32_e32 v29, 0xbfb8aa3b, v29
	v_exp_f32_e32 v30, v29
	v_add_f32_e32 v4, 1.0, v4
	v_add_f32_e32 v5, 1.0, v5
	v_rcp_f32_e32 v4, v4
	v_add_f32_e32 v28, 1.0, v28
	v_rcp_f32_e32 v5, v5
	v_rcp_f32_e32 v29, v28
	v_add_f32_e32 v28, 1.0, v30
	v_rcp_f32_e32 v28, v28
	v_pk_mul_f32 v[32:33], v[4:5], v[2:3]
	v_pk_mul_f32 v[30:31], v[28:29], v[6:7]
	v_add_f32_e32 v32, 0, v32
	v_add_f32_e32 v32, v32, v33
	v_add_f32_e32 v31, v32, v31
	v_add_f32_e32 v30, v31, v30
	s_nop 1
	v_add_f32_dpp v30, v30, v30 quad_perm:[1,0,3,2] row_mask:0xf bank_mask:0xf
	s_nop 1
	v_add_f32_dpp v30, v30, v30 quad_perm:[2,3,0,1] row_mask:0xf bank_mask:0xf
	s_nop 1
	v_add_f32_dpp v30, v30, v30 row_half_mirror row_mask:0xf bank_mask:0xf
	s_nop 1
	v_add_f32_dpp v30, v30, v30 row_mirror row_mask:0xf bank_mask:0xf
	ds_bpermute_b32 v31, v20, v30
	s_waitcnt lgkmcnt(0)
	v_add_f32_e32 v30, v30, v31
	ds_bpermute_b32 v31, v21, v30
	s_waitcnt lgkmcnt(0)
	v_add_f32_e32 v30, v30, v31
	v_mul_f32_e32 v30, 0x3b800000, v30
	v_pk_fma_f32 v[4:5], v[4:5], v[2:3], v[30:31] op_sel_hi:[1,1,0] neg_lo:[0,0,1] neg_hi:[0,0,1]
	v_pk_fma_f32 v[2:3], v[28:29], v[6:7], v[30:31] op_sel_hi:[1,1,0] neg_lo:[0,0,1] neg_hi:[0,0,1]
	v_pk_mul_f32 v[32:33], v[4:5], v[4:5]
	v_pk_mul_f32 v[6:7], v[2:3], v[2:3]
	v_add_f32_e32 v28, v32, v33
	v_add_f32_e32 v7, v7, v28
	v_add_f32_e32 v6, v6, v7
	s_nop 1
	v_add_f32_dpp v6, v6, v6 quad_perm:[1,0,3,2] row_mask:0xf bank_mask:0xf
	s_nop 1
	v_add_f32_dpp v6, v6, v6 quad_perm:[2,3,0,1] row_mask:0xf bank_mask:0xf
	s_nop 1
	v_add_f32_dpp v6, v6, v6 row_half_mirror row_mask:0xf bank_mask:0xf
	s_nop 1
	v_add_f32_dpp v6, v6, v6 row_mirror row_mask:0xf bank_mask:0xf
	ds_bpermute_b32 v7, v20, v6
	s_waitcnt lgkmcnt(0)
	v_add_f32_e32 v6, v6, v7
	ds_bpermute_b32 v7, v21, v6
	s_waitcnt lgkmcnt(0)
	v_add_f32_e32 v6, v6, v7
	v_fmamk_f32 v6, v6, 0x3b800000, v196
	v_mul_f32_e32 v7, 0x4b800000, v6
	v_cmp_gt_f32_e32 vcc, s92, v6
	s_nop 1
	v_cndmask_b32_e32 v6, v6, v7, vcc
	v_rsq_f32_e32 v6, v6
	s_nop 0
	v_mul_f32_e32 v7, 0x45800000, v6
	v_cndmask_b32_e32 v6, v6, v7, vcc
	v_mul_f32_e32 v4, v4, v6
	v_fma_f32 v4, v8, v4, v10
	s_and_b64 vcc, exec, s[16:17]
	v_cvt_pk_bf16_f32 v7, v4, v145
	ds_write_b16 v22, v7 offset:32
	s_cbranch_vccnz .LBB0_398
	v_add_co_u32_e32 v28, vcc, 0x4000, v0
	s_nop 1
	v_addc_co_u32_e32 v29, vcc, 0, v1, vcc
	global_store_dword v[28:29], v4, off

;     __device__ __forceinline__ float* out() const { return (float*)(__attribute__((address_space(1))) float*)ka[32]; }
; __device__ __forceinline__ unsigned cvtpk(float lo, float hi) { unsigned r; asm("v_cvt_pk_bf16_f32 %0, %1, %2" : "=v"(r) : "v"(lo), "v"(hi)); return r; }
; __device__ __forceinline__ float gelu_t(float x) { const float u = 0.7978845608f * (x + 0.044715f * x * x * x); return x * sigm(2.f * u); }
; __device__ __forceinline__ float wave_sum(float v) {
; #pragma unroll
;     for (int o = 1; o < 64; o <<= 1) v += __shfl_xor(v, o);
;     return v;
; }
; __device__ __forceinline__ void phase_branch(const KP2& p, int l, LAS unsigned char* lds) {
;     ...
;                 for (int r4 = 0; r4 < 4; ++r4) { const int i = ib + 8 * r4; if (i < R) {
;                     float v[4]; float s = 0.f;
; #pragma unroll
;                     for (int k = 0; k < 4; ++k) { v[k] = gelu_t(vv[r4][k]); s += v[k]; }
;                     const float mu = wave_sum(s) * (1.f / BW); float q = 0.f;
; #pragma unroll
;                     for (int k = 0; k < 4; ++k) { v[k] -= mu; q += v[k] * v[k]; }
;                     const float rs = rsqrtf(wave_sum(q) * (1.f / BW) + EPS);
; #pragma unroll
;                     for (int k = 0; k < 4; ++k) { const float y = v[k] * rs * gk[k] + bk[k]; vT[(lane + 64 * k) * 136 + i] = (bf16_t)(cvtpk(y, 0.f) & 0xffffu);
;                         if (smp) out[O_AVS + ((size_t)(l * NBS + b) * SSEQ + i) * BW + lane + 64 * k] = y; }
.LBB0_404:
	s_or_b64 exec, exec, s[14:15]
	s_and_saveexec_b64 s[12:13], s[10:11]
	s_cbranch_execz .LBB0_377
	v_lshlrev_b32_e32 v2, 16, v27
	v_mul_f32_e32 v3, 0x3d372713, v2
	v_mul_f32_e32 v3, v3, v2
	v_mov_b32_e32 v4, v2
	v_fmac_f32_e32 v4, v3, v4
	v_mul_f32_e32 v3, 0x3f4c422a, v4
	v_add_f32_e32 v3, v3, v3
	v_mul_f32_e32 v3, 0xbfb8aa3b, v3
	v_exp_f32_e32 v4, v3
	v_lshlrev_b32_e32 v3, 16, v24
	v_mul_f32_e32 v5, 0x3d372713, v3
	v_mul_f32_e32 v5, v5, v3
	v_mov_b32_e32 v24, v3
	v_lshlrev_b32_e32 v7, 16, v25
	v_fmac_f32_e32 v24, v5, v24
	v_mul_f32_e32 v5, 0x3f4c422a, v24
	v_mul_f32_e32 v24, 0x3d372713, v7
	v_mul_f32_e32 v24, v24, v7
	v_mov_b32_e32 v25, v7
	v_lshlrev_b32_e32 v6, 16, v26
	v_fmac_f32_e32 v25, v24, v25
	v_mul_f32_e32 v24, 0x3f4c422a, v25
	v_mul_f32_e32 v25, 0x3d372713, v6
	v_mul_f32_e32 v25, v25, v6
	v_mov_b32_e32 v26, v6
	v_add_f32_e32 v5, v5, v5
	v_fmac_f32_e32 v26, v25, v26
	v_mul_f32_e32 v5, 0xbfb8aa3b, v5
	v_add_f32_e32 v24, v24, v24
	v_mul_f32_e32 v25, 0x3f4c422a, v26
	v_exp_f32_e32 v5, v5
	v_mul_f32_e32 v24, 0xbfb8aa3b, v24
	v_add_f32_e32 v25, v25, v25
	v_exp_f32_e32 v24, v24
	v_mul_f32_e32 v25, 0xbfb8aa3b, v25
	v_exp_f32_e32 v26, v25
	v_add_f32_e32 v4, 1.0, v4
	v_add_f32_e32 v5, 1.0, v5
	v_rcp_f32_e32 v4, v4
	v_add_f32_e32 v24, 1.0, v24
	v_rcp_f32_e32 v5, v5
	v_rcp_f32_e32 v25, v24
	v_add_f32_e32 v24, 1.0, v26
	v_rcp_f32_e32 v24, v24
	v_pk_mul_f32 v[28:29], v[4:5], v[2:3]
	v_pk_mul_f32 v[26:27], v[24:25], v[6:7]
	v_add_f32_e32 v28, 0, v28
	v_add_f32_e32 v28, v28, v29
	v_add_f32_e32 v27, v28, v27
	v_add_f32_e32 v26, v27, v26
	s_nop 1
	v_add_f32_dpp v26, v26, v26 quad_perm:[1,0,3,2] row_mask:0xf bank_mask:0xf
	s_nop 1
	v_add_f32_dpp v26, v26, v26 quad_perm:[2,3,0,1] row_mask:0xf bank_mask:0xf
	s_nop 1
	v_add_f32_dpp v26, v26, v26 row_half_mirror row_mask:0xf bank_mask:0xf
	s_nop 1
	v_add_f32_dpp v26, v26, v26 row_mirror row_mask:0xf bank_mask:0xf
	ds_bpermute_b32 v27, v20, v26
	s_waitcnt lgkmcnt(0)
	v_add_f32_e32 v26, v26, v27
	ds_bpermute_b32 v27, v21, v26
	s_waitcnt lgkmcnt(0)
	v_add_f32_e32 v26, v26, v27
	v_mul_f32_e32 v26, 0x3b800000, v26
	v_pk_fma_f32 v[4:5], v[4:5], v[2:3], v[26:27] op_sel_hi:[1,1,0] neg_lo:[0,0,1] neg_hi:[0,0,1]
	v_pk_fma_f32 v[2:3], v[24:25], v[6:7], v[26:27] op_sel_hi:[1,1,0] neg_lo:[0,0,1] neg_hi:[0,0,1]
	v_pk_mul_f32 v[28:29], v[4:5], v[4:5]
	v_pk_mul_f32 v[6:7], v[2:3], v[2:3]
	v_add_f32_e32 v24, v28, v29
	v_add_f32_e32 v7, v7, v24
	v_add_f32_e32 v6, v6, v7
	s_nop 1
	v_add_f32_dpp v6, v6, v6 quad_perm:[1,0,3,2] row_mask:0xf bank_mask:0xf
	s_nop 1
	v_add_f32_dpp v6, v6, v6 quad_perm:[2,3,0,1] row_mask:0xf bank_mask:0xf
	s_nop 1
	v_add_f32_dpp v6, v6, v6 row_half_mirror row_mask:0xf bank_mask:0xf
	s_nop 1
	v_add_f32_dpp v6, v6, v6 row_mirror row_mask:0xf bank_mask:0xf
	ds_bpermute_b32 v7, v20, v6
	s_waitcnt lgkmcnt(0)
	v_add_f32_e32 v6, v6, v7
	ds_bpermute_b32 v7, v21, v6
	s_waitcnt lgkmcnt(0)
	v_add_f32_e32 v6, v6, v7
	v_fmamk_f32 v6, v6, 0x3b800000, v196
	v_mul_f32_e32 v7, 0x4b800000, v6
	v_cmp_gt_f32_e32 vcc, s92, v6
	s_nop 1
	v_cndmask_b32_e32 v6, v6, v7, vcc
	v_rsq_f32_e32 v6, v6
	s_nop 0
	v_mul_f32_e32 v7, 0x45800000, v6
	v_cndmask_b32_e32 v6, v6, v7, vcc
	v_mul_f32_e32 v4, v4, v6
	v_fma_f32 v4, v8, v4, v10
	s_and_b64 vcc, exec, s[16:17]
	v_cvt_pk_bf16_f32 v7, v4, v145
	ds_write_b16 v22, v7 offset:48
	s_cbranch_vccnz .LBB0_407
	v_add_co_u32_e32 v24, vcc, 0x6000, v0
	s_nop 1
	v_addc_co_u32_e32 v25, vcc, 0, v1, vcc
	global_store_dword v[24:25], v4, off

; #define LAS __attribute__((address_space(3)))
; __device__ __forceinline__ float bflo(unsigned w) { return __uint_as_float(w << 16); }
; __device__ __forceinline__ float bfhi(unsigned w) { return __uint_as_float(w & 0xffff0000u); }
; __device__ __forceinline__ void phase_branch(const KP2& p, int l, LAS unsigned char* lds) {
;     ...
;                     for (int kc = 0; kc < 4; ++kc) {
;                         asm volatile("" ::: "memory");
;                         f32x4 x[15];
; #pragma unroll
;                         for (int rr = 0; rr < 15; ++rr) if (kc < 3 || rr < 14) { const u32x2 v = *(const LAS u32x2*)(tile + (tb + 8 * kc + rr) * 512 + lane * 8); x[rr] = (f32x4){bflo(v.x), bfhi(v.x), bflo(v.y), bfhi(v.y)}; }
; #pragma unroll
;                         for (int kk = 0; kk < 8; ++kk) if (8 * kc + kk < 31) { const f32x4 wk = ((const LAS f32x4*)wl)[(8 * kc + kk) * 64 + lane];
; #pragma unroll
;                             for (int t = 0; t < 8; ++t) acc[t] += wk * x[t + kk]; }
.LBB0_436:
	v_or_b32_e32 v144, s16, v215
	v_lshl_add_u32 v44, v144, 9, v217
	ds_read2st64_b64 v[12:15], v44 offset1:1
	s_waitcnt lgkmcnt(0)
	v_lshlrev_b32_e32 v16, 16, v12
	v_and_b32_e32 v17, 0xffff0000, v12
	v_lshlrev_b32_e32 v18, 16, v13
	v_and_b32_e32 v19, 0xffff0000, v13
	v_lshlrev_b32_e32 v20, 16, v14
	v_and_b32_e32 v21, 0xffff0000, v14
	v_lshlrev_b32_e32 v22, 16, v15
	v_and_b32_e32 v23, 0xffff0000, v15
	ds_read2st64_b64 v[12:15], v44 offset0:2 offset1:3
	s_waitcnt lgkmcnt(0)
	v_lshlrev_b32_e32 v24, 16, v12
	v_and_b32_e32 v25, 0xffff0000, v12
	v_lshlrev_b32_e32 v26, 16, v13
	v_and_b32_e32 v27, 0xffff0000, v13
	v_lshlrev_b32_e32 v28, 16, v14
	v_and_b32_e32 v29, 0xffff0000, v14
	v_lshlrev_b32_e32 v30, 16, v15
	v_and_b32_e32 v31, 0xffff0000, v15
	ds_read2st64_b64 v[12:15], v44 offset0:4 offset1:5
	s_waitcnt lgkmcnt(0)
	v_lshlrev_b32_e32 v32, 16, v12
	v_and_b32_e32 v33, 0xffff0000, v12
	v_lshlrev_b32_e32 v34, 16, v13
	v_and_b32_e32 v35, 0xffff0000, v13
	v_lshlrev_b32_e32 v36, 16, v14
	v_and_b32_e32 v37, 0xffff0000, v14
	v_lshlrev_b32_e32 v38, 16, v15
	v_and_b32_e32 v39, 0xffff0000, v15
	ds_read2st64_b64 v[12:15], v44 offset0:6 offset1:7
	s_waitcnt lgkmcnt(0)
	v_lshlrev_b32_e32 v40, 16, v12
	v_and_b32_e32 v41, 0xffff0000, v12
	v_lshlrev_b32_e32 v42, 16, v13
	v_and_b32_e32 v43, 0xffff0000, v13
	v_lshlrev_b32_e32 v46, 16, v14
	v_and_b32_e32 v47, 0xffff0000, v14
	v_lshlrev_b32_e32 v48, 16, v15
	v_and_b32_e32 v49, 0xffff0000, v15
	ds_read2st64_b64 v[12:15], v44 offset0:8 offset1:9
	s_waitcnt lgkmcnt(0)
	v_lshlrev_b32_e32 v50, 16, v12
	v_and_b32_e32 v51, 0xffff0000, v12
	v_lshlrev_b32_e32 v52, 16, v13
	v_and_b32_e32 v53, 0xffff0000, v13
	v_lshlrev_b32_e32 v54, 16, v14
	v_and_b32_e32 v55, 0xffff0000, v14
	v_lshlrev_b32_e32 v56, 16, v15
	v_and_b32_e32 v57, 0xffff0000, v15
	ds_read2st64_b64 v[12:15], v44 offset0:10 offset1:11
	s_waitcnt lgkmcnt(0)
	v_lshlrev_b32_e32 v58, 16, v12
	v_and_b32_e32 v59, 0xffff0000, v12
	v_lshlrev_b32_e32 v60, 16, v13
	v_and_b32_e32 v61, 0xffff0000, v13
	v_lshlrev_b32_e32 v62, 16, v14
	v_and_b32_e32 v63, 0xffff0000, v14
	v_lshlrev_b32_e32 v64, 16, v15
	v_and_b32_e32 v65, 0xffff0000, v15
	ds_read2st64_b64 v[12:15], v44 offset0:12 offset1:13
	s_waitcnt lgkmcnt(0)
	v_lshlrev_b32_e32 v66, 16, v12
	v_and_b32_e32 v67, 0xffff0000, v12
	v_lshlrev_b32_e32 v162, 16, v13
	v_and_b32_e32 v163, 0xffff0000, v13
	ds_read_b64 v[12:13], v44 offset:7168
	v_lshlrev_b32_e32 v164, 16, v14
	v_and_b32_e32 v165, 0xffff0000, v14
	v_lshlrev_b32_e32 v166, 16, v15
	v_and_b32_e32 v167, 0xffff0000, v15
	s_waitcnt lgkmcnt(0)
	v_lshlrev_b32_e32 v168, 16, v12
	v_and_b32_e32 v169, 0xffff0000, v12
	v_lshlrev_b32_e32 v170, 16, v13
	v_and_b32_e32 v171, 0xffff0000, v13
	ds_read_b128 v[12:15], v218
	s_waitcnt lgkmcnt(0)
	v_pk_fma_f32 v[18:19], v[14:15], v[18:19], v[2:3]
	v_pk_fma_f32 v[16:17], v[12:13], v[16:17], v[0:1]
	v_pk_fma_f32 v[44:45], v[14:15], v[22:23], v[2:3]
	v_pk_fma_f32 v[172:173], v[12:13], v[20:21], v[0:1]
	v_pk_fma_f32 v[174:175], v[14:15], v[26:27], v[2:3]
	v_pk_fma_f32 v[176:177], v[12:13], v[24:25], v[0:1]
	v_pk_fma_f32 v[178:179], v[14:15], v[30:31], v[2:3]
	v_pk_fma_f32 v[180:181], v[12:13], v[28:29], v[0:1]
	v_pk_fma_f32 v[182:183], v[14:15], v[34:35], v[2:3]
	v_pk_fma_f32 v[184:185], v[12:13], v[32:33], v[0:1]
	v_pk_fma_f32 v[186:187], v[14:15], v[38:39], v[2:3]
	v_pk_fma_f32 v[188:189], v[12:13], v[36:37], v[0:1]
	v_pk_fma_f32 v[190:191], v[14:15], v[42:43], v[2:3]
	v_pk_fma_f32 v[192:193], v[12:13], v[40:41], v[0:1]
	v_pk_fma_f32 v[198:199], v[14:15], v[48:49], v[2:3]
	v_pk_fma_f32 v[200:201], v[12:13], v[46:47], v[0:1]
	ds_read_b128 v[12:15], v218 offset:1024
	s_waitcnt lgkmcnt(0)
	v_pk_fma_f32 v[16:17], v[12:13], v[20:21], v[16:17]
	v_pk_fma_f32 v[18:19], v[14:15], v[22:23], v[18:19]
	v_pk_fma_f32 v[20:21], v[12:13], v[24:25], v[172:173]
	v_pk_fma_f32 v[22:23], v[14:15], v[26:27], v[44:45]
	v_pk_fma_f32 v[44:45], v[12:13], v[28:29], v[176:177]
	v_pk_fma_f32 v[172:173], v[14:15], v[30:31], v[174:175]
	v_pk_fma_f32 v[174:175], v[12:13], v[32:33], v[180:181]
	v_pk_fma_f32 v[176:177], v[14:15], v[34:35], v[178:179]
	v_pk_fma_f32 v[178:179], v[12:13], v[36:37], v[184:185]
	v_pk_fma_f32 v[180:181], v[14:15], v[38:39], v[182:183]
	v_pk_fma_f32 v[182:183], v[12:13], v[40:41], v[188:189]
	v_pk_fma_f32 v[184:185], v[14:15], v[42:43], v[186:187]
	v_pk_fma_f32 v[186:187], v[12:13], v[46:47], v[192:193]
	v_pk_fma_f32 v[188:189], v[14:15], v[48:49], v[190:191]
	v_pk_fma_f32 v[190:191], v[12:13], v[50:51], v[200:201]
	v_pk_fma_f32 v[192:193], v[14:15], v[52:53], v[198:199]
	ds_read_b128 v[12:15], v218 offset:2048
	s_waitcnt lgkmcnt(0)
	v_pk_fma_f32 v[18:19], v[14:15], v[26:27], v[18:19]
	v_pk_fma_f32 v[16:17], v[12:13], v[24:25], v[16:17]
	v_pk_fma_f32 v[22:23], v[14:15], v[30:31], v[22:23]
	v_pk_fma_f32 v[20:21], v[12:13], v[28:29], v[20:21]
	v_pk_fma_f32 v[24:25], v[14:15], v[34:35], v[172:173]
	v_pk_fma_f32 v[26:27], v[12:13], v[32:33], v[44:45]
	v_pk_fma_f32 v[44:45], v[14:15], v[38:39], v[176:177]
	v_pk_fma_f32 v[172:173], v[12:13], v[36:37], v[174:175]
	v_pk_fma_f32 v[174:175], v[14:15], v[42:43], v[180:181]
	v_pk_fma_f32 v[176:177], v[12:13], v[40:41], v[178:179]
	v_pk_fma_f32 v[178:179], v[14:15], v[48:49], v[184:185]
	v_pk_fma_f32 v[180:181], v[12:13], v[46:47], v[182:183]
	v_pk_fma_f32 v[182:183], v[14:15], v[52:53], v[188:189]
	v_pk_fma_f32 v[184:185], v[12:13], v[50:51], v[186:187]
	v_pk_fma_f32 v[186:187], v[14:15], v[56:57], v[192:193]
	v_pk_fma_f32 v[188:189], v[12:13], v[54:55], v[190:191]
	ds_read_b128 v[12:15], v218 offset:3072
	s_waitcnt lgkmcnt(0)
; #define LAS __attribute__((address_space(3)))
; __device__ __forceinline__ float bflo(unsigned w) { return __uint_as_float(w << 16); }
; __device__ __forceinline__ float bfhi(unsigned w) { return __uint_as_float(w & 0xffff0000u); }
; __device__ __forceinline__ void phase_branch(const KP2& p, int l, LAS unsigned char* lds) {
;     ...
;                     for (int kc = 0; kc < 4; ++kc) {
;                         asm volatile("" ::: "memory");
;                         f32x4 x[15];
; #pragma unroll
;                         for (int rr = 0; rr < 15; ++rr) if (kc < 3 || rr < 14) { const u32x2 v = *(const LAS u32x2*)(tile + (tb + 8 * kc + rr) * 512 + lane * 8); x[rr] = (f32x4){bflo(v.x), bfhi(v.x), bflo(v.y), bfhi(v.y)}; }
; #pragma unroll
;                         for (int kk = 0; kk < 8; ++kk) if (8 * kc + kk < 31) { const f32x4 wk = ((const LAS f32x4*)wl)[(8 * kc + kk) * 64 + lane];
; #pragma unroll
;                             for (int t = 0; t < 8; ++t) acc[t] += wk * x[t + kk]; }
	v_pk_fma_f32 v[16:17], v[12:13], v[28:29], v[16:17]
	v_pk_fma_f32 v[18:19], v[14:15], v[30:31], v[18:19]
	v_pk_fma_f32 v[20:21], v[12:13], v[32:33], v[20:21]
	v_pk_fma_f32 v[22:23], v[14:15], v[34:35], v[22:23]
	v_pk_fma_f32 v[26:27], v[12:13], v[36:37], v[26:27]
	v_pk_fma_f32 v[24:25], v[14:15], v[38:39], v[24:25]
	v_pk_fma_f32 v[28:29], v[12:13], v[40:41], v[172:173]
	v_pk_fma_f32 v[30:31], v[14:15], v[42:43], v[44:45]
	v_pk_fma_f32 v[44:45], v[12:13], v[46:47], v[176:177]
	v_pk_fma_f32 v[172:173], v[14:15], v[48:49], v[174:175]
	v_pk_fma_f32 v[174:175], v[12:13], v[50:51], v[180:181]
	v_pk_fma_f32 v[176:177], v[14:15], v[52:53], v[178:179]
	v_pk_fma_f32 v[178:179], v[12:13], v[54:55], v[184:185]
	v_pk_fma_f32 v[180:181], v[14:15], v[56:57], v[182:183]
	v_pk_fma_f32 v[182:183], v[12:13], v[58:59], v[188:189]
	v_pk_fma_f32 v[184:185], v[14:15], v[60:61], v[186:187]
	ds_read_b128 v[12:15], v218 offset:4096
	s_waitcnt lgkmcnt(0)
	v_pk_fma_f32 v[18:19], v[14:15], v[34:35], v[18:19]
	v_pk_fma_f32 v[16:17], v[12:13], v[32:33], v[16:17]
	v_pk_fma_f32 v[22:23], v[14:15], v[38:39], v[22:23]
	v_pk_fma_f32 v[20:21], v[12:13], v[36:37], v[20:21]
	v_pk_fma_f32 v[24:25], v[14:15], v[42:43], v[24:25]
	v_pk_fma_f32 v[26:27], v[12:13], v[40:41], v[26:27]
	v_pk_fma_f32 v[30:31], v[14:15], v[48:49], v[30:31]
	v_pk_fma_f32 v[28:29], v[12:13], v[46:47], v[28:29]
	v_pk_fma_f32 v[32:33], v[14:15], v[52:53], v[172:173]
	v_pk_fma_f32 v[34:35], v[12:13], v[50:51], v[44:45]
	v_pk_fma_f32 v[44:45], v[14:15], v[56:57], v[176:177]
	v_pk_fma_f32 v[172:173], v[12:13], v[54:55], v[174:175]
	v_pk_fma_f32 v[174:175], v[14:15], v[60:61], v[180:181]
	v_pk_fma_f32 v[176:177], v[12:13], v[58:59], v[178:179]
	v_pk_fma_f32 v[178:179], v[14:15], v[64:65], v[184:185]
	v_pk_fma_f32 v[180:181], v[12:13], v[62:63], v[182:183]
	ds_read_b128 v[12:15], v218 offset:5120
	s_waitcnt lgkmcnt(0)
	v_pk_fma_f32 v[16:17], v[12:13], v[36:37], v[16:17]
	v_pk_fma_f32 v[18:19], v[14:15], v[38:39], v[18:19]
	v_pk_fma_f32 v[20:21], v[12:13], v[40:41], v[20:21]
	v_pk_fma_f32 v[22:23], v[14:15], v[42:43], v[22:23]
	v_pk_fma_f32 v[26:27], v[12:13], v[46:47], v[26:27]
	v_pk_fma_f32 v[24:25], v[14:15], v[48:49], v[24:25]
	v_pk_fma_f32 v[28:29], v[12:13], v[50:51], v[28:29]
	v_pk_fma_f32 v[30:31], v[14:15], v[52:53], v[30:31]
	v_pk_fma_f32 v[34:35], v[12:13], v[54:55], v[34:35]
	v_pk_fma_f32 v[32:33], v[14:15], v[56:57], v[32:33]
	v_pk_fma_f32 v[36:37], v[12:13], v[58:59], v[172:173]
	v_pk_fma_f32 v[38:39], v[14:15], v[60:61], v[44:45]
	v_pk_fma_f32 v[44:45], v[12:13], v[62:63], v[176:177]
	v_pk_fma_f32 v[172:173], v[14:15], v[64:65], v[174:175]
	v_pk_fma_f32 v[174:175], v[12:13], v[66:67], v[180:181]
	v_pk_fma_f32 v[176:177], v[14:15], v[162:163], v[178:179]
	ds_read_b128 v[12:15], v218 offset:6144
	s_waitcnt lgkmcnt(0)
	v_pk_fma_f32 v[18:19], v[14:15], v[42:43], v[18:19]
	v_pk_fma_f32 v[186:187], v[12:13], v[66:67], v[44:45]
	ds_read_b128 v[42:45], v218 offset:7168
	v_pk_fma_f32 v[16:17], v[12:13], v[40:41], v[16:17]
	v_pk_fma_f32 v[22:23], v[14:15], v[48:49], v[22:23]
	v_pk_fma_f32 v[20:21], v[12:13], v[46:47], v[20:21]
	v_pk_fma_f32 v[24:25], v[14:15], v[52:53], v[24:25]
	v_pk_fma_f32 v[26:27], v[12:13], v[50:51], v[26:27]
	v_pk_fma_f32 v[40:41], v[14:15], v[56:57], v[30:31]
	v_pk_fma_f32 v[178:179], v[12:13], v[54:55], v[28:29]
	v_pk_fma_f32 v[180:181], v[14:15], v[60:61], v[32:33]
	v_pk_fma_f32 v[182:183], v[12:13], v[58:59], v[34:35]
	v_pk_fma_f32 v[38:39], v[14:15], v[64:65], v[38:39]
	v_pk_fma_f32 v[184:185], v[12:13], v[62:63], v[36:37]
	v_pk_fma_f32 v[172:173], v[14:15], v[162:163], v[172:173]
	v_pk_fma_f32 v[176:177], v[14:15], v[166:167], v[176:177]
	v_pk_fma_f32 v[174:175], v[12:13], v[164:165], v[174:175]
	s_waitcnt lgkmcnt(0)
	v_pk_fma_f32 v[12:13], v[42:43], v[46:47], v[16:17]
	v_pk_fma_f32 v[28:29], v[44:45], v[48:49], v[18:19]
	v_pk_fma_f32 v[14:15], v[42:43], v[50:51], v[20:21]
	v_pk_fma_f32 v[30:31], v[44:45], v[52:53], v[22:23]
	v_pk_fma_f32 v[16:17], v[42:43], v[54:55], v[26:27]
	v_pk_fma_f32 v[32:33], v[44:45], v[56:57], v[24:25]
	v_pk_fma_f32 v[18:19], v[42:43], v[58:59], v[178:179]
	v_pk_fma_f32 v[34:35], v[44:45], v[60:61], v[40:41]
	v_pk_fma_f32 v[20:21], v[42:43], v[62:63], v[182:183]
	v_pk_fma_f32 v[36:37], v[44:45], v[64:65], v[180:181]
	v_pk_fma_f32 v[22:23], v[42:43], v[66:67], v[184:185]
	v_pk_fma_f32 v[38:39], v[44:45], v[162:163], v[38:39]
	v_pk_fma_f32 v[24:25], v[42:43], v[164:165], v[186:187]
	v_pk_fma_f32 v[40:41], v[44:45], v[166:167], v[172:173]
	v_pk_fma_f32 v[26:27], v[42:43], v[168:169], v[174:175]
	v_pk_fma_f32 v[42:43], v[44:45], v[170:171], v[176:177]
	v_add_u32_e32 v44, s16, v226
	v_lshl_add_u32 v204, v44, 9, v217
	ds_read2st64_b64 v[44:47], v204 offset1:1
	s_waitcnt lgkmcnt(0)
	v_lshlrev_b32_e32 v48, 16, v44
	v_and_b32_e32 v49, 0xffff0000, v44
	v_lshlrev_b32_e32 v50, 16, v45
	v_and_b32_e32 v51, 0xffff0000, v45
	v_lshlrev_b32_e32 v52, 16, v46
	v_and_b32_e32 v53, 0xffff0000, v46
	v_lshlrev_b32_e32 v54, 16, v47
	v_and_b32_e32 v55, 0xffff0000, v47
	ds_read2st64_b64 v[44:47], v204 offset0:2 offset1:3
	s_waitcnt lgkmcnt(0)
	v_lshlrev_b32_e32 v56, 16, v44
	v_and_b32_e32 v57, 0xffff0000, v44
	v_lshlrev_b32_e32 v58, 16, v45
	v_and_b32_e32 v59, 0xffff0000, v45
	v_lshlrev_b32_e32 v60, 16, v46
	v_and_b32_e32 v61, 0xffff0000, v46
	v_lshlrev_b32_e32 v62, 16, v47
	v_and_b32_e32 v63, 0xffff0000, v47
	ds_read2st64_b64 v[44:47], v204 offset0:4 offset1:5
	s_waitcnt lgkmcnt(0)
	v_lshlrev_b32_e32 v64, 16, v44
	v_and_b32_e32 v65, 0xffff0000, v44
	v_lshlrev_b32_e32 v66, 16, v45
	v_and_b32_e32 v67, 0xffff0000, v45
	v_lshlrev_b32_e32 v162, 16, v46
	v_and_b32_e32 v163, 0xffff0000, v46
	v_lshlrev_b32_e32 v164, 16, v47
	v_and_b32_e32 v165, 0xffff0000, v47
	ds_read2st64_b64 v[44:47], v204 offset0:6 offset1:7
	s_waitcnt lgkmcnt(0)
; #define LAS __attribute__((address_space(3)))
; __device__ __forceinline__ float bflo(unsigned w) { return __uint_as_float(w << 16); }
; __device__ __forceinline__ float bfhi(unsigned w) { return __uint_as_float(w & 0xffff0000u); }
; __device__ __forceinline__ void phase_branch(const KP2& p, int l, LAS unsigned char* lds) {
;     ...
;                     for (int kc = 0; kc < 4; ++kc) {
;                         asm volatile("" ::: "memory");
;                         f32x4 x[15];
; #pragma unroll
;                         for (int rr = 0; rr < 15; ++rr) if (kc < 3 || rr < 14) { const u32x2 v = *(const LAS u32x2*)(tile + (tb + 8 * kc + rr) * 512 + lane * 8); x[rr] = (f32x4){bflo(v.x), bfhi(v.x), bflo(v.y), bfhi(v.y)}; }
; #pragma unroll
;                         for (int kk = 0; kk < 8; ++kk) if (8 * kc + kk < 31) { const f32x4 wk = ((const LAS f32x4*)wl)[(8 * kc + kk) * 64 + lane];
; #pragma unroll
;                             for (int t = 0; t < 8; ++t) acc[t] += wk * x[t + kk]; }
	v_lshlrev_b32_e32 v166, 16, v44
	v_and_b32_e32 v167, 0xffff0000, v44
	v_lshlrev_b32_e32 v168, 16, v45
	v_and_b32_e32 v169, 0xffff0000, v45
	v_lshlrev_b32_e32 v170, 16, v46
	v_and_b32_e32 v171, 0xffff0000, v46
	v_lshlrev_b32_e32 v172, 16, v47
	v_and_b32_e32 v173, 0xffff0000, v47
	ds_read2st64_b64 v[44:47], v204 offset0:8 offset1:9
	s_waitcnt lgkmcnt(0)
	v_lshlrev_b32_e32 v174, 16, v44
	v_and_b32_e32 v175, 0xffff0000, v44
	v_lshlrev_b32_e32 v176, 16, v45
	v_and_b32_e32 v177, 0xffff0000, v45
	v_lshlrev_b32_e32 v178, 16, v46
	v_and_b32_e32 v179, 0xffff0000, v46
	v_lshlrev_b32_e32 v180, 16, v47
	v_and_b32_e32 v181, 0xffff0000, v47
	ds_read2st64_b64 v[44:47], v204 offset0:10 offset1:11
	s_waitcnt lgkmcnt(0)
	v_lshlrev_b32_e32 v182, 16, v44
	v_and_b32_e32 v183, 0xffff0000, v44
	v_lshlrev_b32_e32 v184, 16, v45
	v_and_b32_e32 v185, 0xffff0000, v45
	v_lshlrev_b32_e32 v186, 16, v46
	v_and_b32_e32 v187, 0xffff0000, v46
	v_lshlrev_b32_e32 v188, 16, v47
	v_and_b32_e32 v189, 0xffff0000, v47
	ds_read2st64_b64 v[44:47], v204 offset0:12 offset1:13
	s_waitcnt lgkmcnt(0)
	v_lshlrev_b32_e32 v190, 16, v44
	v_and_b32_e32 v191, 0xffff0000, v44
	v_lshlrev_b32_e32 v192, 16, v45
	v_and_b32_e32 v193, 0xffff0000, v45
	ds_read_b64 v[44:45], v204 offset:7168
	v_lshlrev_b32_e32 v198, 16, v46
	v_and_b32_e32 v199, 0xffff0000, v46
	v_lshlrev_b32_e32 v200, 16, v47
	v_and_b32_e32 v201, 0xffff0000, v47
	s_waitcnt lgkmcnt(0)
	v_lshlrev_b32_e32 v204, 16, v44
	v_and_b32_e32 v205, 0xffff0000, v44
	v_lshlrev_b32_e32 v206, 16, v45
	v_and_b32_e32 v207, 0xffff0000, v45
	ds_read_b128 v[44:47], v218 offset:8192
	s_waitcnt lgkmcnt(0)
	v_pk_fma_f32 v[28:29], v[46:47], v[50:51], v[28:29]
	v_pk_fma_f32 v[48:49], v[44:45], v[48:49], v[12:13]
	v_pk_fma_f32 v[50:51], v[44:45], v[52:53], v[14:15]
	ds_read_b128 v[12:15], v218 offset:9216
	v_pk_fma_f32 v[30:31], v[46:47], v[54:55], v[30:31]
	v_pk_fma_f32 v[32:33], v[46:47], v[58:59], v[32:33]
	v_pk_fma_f32 v[16:17], v[44:45], v[56:57], v[16:17]
	v_pk_fma_f32 v[34:35], v[46:47], v[62:63], v[34:35]
	v_pk_fma_f32 v[18:19], v[44:45], v[60:61], v[18:19]
	v_pk_fma_f32 v[36:37], v[46:47], v[66:67], v[36:37]
	v_pk_fma_f32 v[20:21], v[44:45], v[64:65], v[20:21]
	v_pk_fma_f32 v[38:39], v[46:47], v[164:165], v[38:39]
	v_pk_fma_f32 v[22:23], v[44:45], v[162:163], v[22:23]
	v_pk_fma_f32 v[40:41], v[46:47], v[168:169], v[40:41]
	v_pk_fma_f32 v[24:25], v[44:45], v[166:167], v[24:25]
	v_pk_fma_f32 v[42:43], v[46:47], v[172:173], v[42:43]
	v_pk_fma_f32 v[26:27], v[44:45], v[170:171], v[26:27]
	s_waitcnt lgkmcnt(0)
	v_pk_fma_f32 v[44:45], v[12:13], v[52:53], v[48:49]
	v_pk_fma_f32 v[28:29], v[14:15], v[54:55], v[28:29]
	v_pk_fma_f32 v[46:47], v[12:13], v[56:57], v[50:51]
	v_pk_fma_f32 v[30:31], v[14:15], v[58:59], v[30:31]
	v_pk_fma_f32 v[16:17], v[12:13], v[60:61], v[16:17]
	v_pk_fma_f32 v[32:33], v[14:15], v[62:63], v[32:33]
	v_pk_fma_f32 v[18:19], v[12:13], v[64:65], v[18:19]
	v_pk_fma_f32 v[34:35], v[14:15], v[66:67], v[34:35]
	v_pk_fma_f32 v[20:21], v[12:13], v[162:163], v[20:21]
	v_pk_fma_f32 v[36:37], v[14:15], v[164:165], v[36:37]
	v_pk_fma_f32 v[22:23], v[12:13], v[166:167], v[22:23]
	v_pk_fma_f32 v[38:39], v[14:15], v[168:169], v[38:39]
	v_pk_fma_f32 v[24:25], v[12:13], v[170:171], v[24:25]
	v_pk_fma_f32 v[40:41], v[14:15], v[172:173], v[40:41]
	v_pk_fma_f32 v[26:27], v[12:13], v[174:175], v[26:27]
	v_pk_fma_f32 v[42:43], v[14:15], v[176:177], v[42:43]
	ds_read_b128 v[12:15], v218 offset:10240
	s_waitcnt lgkmcnt(0)
	v_pk_fma_f32 v[28:29], v[14:15], v[58:59], v[28:29]
	v_pk_fma_f32 v[44:45], v[12:13], v[56:57], v[44:45]
	v_pk_fma_f32 v[30:31], v[14:15], v[62:63], v[30:31]
	v_pk_fma_f32 v[46:47], v[12:13], v[60:61], v[46:47]
	v_pk_fma_f32 v[32:33], v[14:15], v[66:67], v[32:33]
	v_pk_fma_f32 v[16:17], v[12:13], v[64:65], v[16:17]
	v_pk_fma_f32 v[34:35], v[14:15], v[164:165], v[34:35]
	v_pk_fma_f32 v[18:19], v[12:13], v[162:163], v[18:19]
	v_pk_fma_f32 v[36:37], v[14:15], v[168:169], v[36:37]
	v_pk_fma_f32 v[20:21], v[12:13], v[166:167], v[20:21]
	v_pk_fma_f32 v[38:39], v[14:15], v[172:173], v[38:39]
	v_pk_fma_f32 v[22:23], v[12:13], v[170:171], v[22:23]
	v_pk_fma_f32 v[40:41], v[14:15], v[176:177], v[40:41]
	v_pk_fma_f32 v[24:25], v[12:13], v[174:175], v[24:25]
	v_pk_fma_f32 v[42:43], v[14:15], v[180:181], v[42:43]
	v_pk_fma_f32 v[26:27], v[12:13], v[178:179], v[26:27]
	ds_read_b128 v[12:15], v218 offset:11264
	s_waitcnt lgkmcnt(0)
	v_pk_fma_f32 v[44:45], v[12:13], v[60:61], v[44:45]
	v_pk_fma_f32 v[28:29], v[14:15], v[62:63], v[28:29]
	v_pk_fma_f32 v[46:47], v[12:13], v[64:65], v[46:47]
	v_pk_fma_f32 v[30:31], v[14:15], v[66:67], v[30:31]
	v_pk_fma_f32 v[16:17], v[12:13], v[162:163], v[16:17]
	v_pk_fma_f32 v[32:33], v[14:15], v[164:165], v[32:33]
	v_pk_fma_f32 v[18:19], v[12:13], v[166:167], v[18:19]
	v_pk_fma_f32 v[34:35], v[14:15], v[168:169], v[34:35]
	v_pk_fma_f32 v[20:21], v[12:13], v[170:171], v[20:21]
	v_pk_fma_f32 v[36:37], v[14:15], v[172:173], v[36:37]
	v_pk_fma_f32 v[22:23], v[12:13], v[174:175], v[22:23]
	v_pk_fma_f32 v[38:39], v[14:15], v[176:177], v[38:39]
	v_pk_fma_f32 v[24:25], v[12:13], v[178:179], v[24:25]
	v_pk_fma_f32 v[40:41], v[14:15], v[180:181], v[40:41]
	v_pk_fma_f32 v[26:27], v[12:13], v[182:183], v[26:27]
	v_pk_fma_f32 v[42:43], v[14:15], v[184:185], v[42:43]
	ds_read_b128 v[12:15], v218 offset:12288
	s_waitcnt lgkmcnt(0)
; #define LAS __attribute__((address_space(3)))
; __device__ __forceinline__ float bflo(unsigned w) { return __uint_as_float(w << 16); }
; __device__ __forceinline__ float bfhi(unsigned w) { return __uint_as_float(w & 0xffff0000u); }
; __device__ __forceinline__ void phase_branch(const KP2& p, int l, LAS unsigned char* lds) {
;     ...
;                     for (int kc = 0; kc < 4; ++kc) {
;                         asm volatile("" ::: "memory");
;                         f32x4 x[15];
; #pragma unroll
;                         for (int rr = 0; rr < 15; ++rr) if (kc < 3 || rr < 14) { const u32x2 v = *(const LAS u32x2*)(tile + (tb + 8 * kc + rr) * 512 + lane * 8); x[rr] = (f32x4){bflo(v.x), bfhi(v.x), bflo(v.y), bfhi(v.y)}; }
; #pragma unroll
;                         for (int kk = 0; kk < 8; ++kk) if (8 * kc + kk < 31) { const f32x4 wk = ((const LAS f32x4*)wl)[(8 * kc + kk) * 64 + lane];
; #pragma unroll
;                             for (int t = 0; t < 8; ++t) acc[t] += wk * x[t + kk]; }
	v_pk_fma_f32 v[28:29], v[14:15], v[66:67], v[28:29]
	v_pk_fma_f32 v[44:45], v[12:13], v[64:65], v[44:45]
	v_pk_fma_f32 v[30:31], v[14:15], v[164:165], v[30:31]
	v_pk_fma_f32 v[46:47], v[12:13], v[162:163], v[46:47]
	v_pk_fma_f32 v[32:33], v[14:15], v[168:169], v[32:33]
	v_pk_fma_f32 v[16:17], v[12:13], v[166:167], v[16:17]
	v_pk_fma_f32 v[34:35], v[14:15], v[172:173], v[34:35]
	v_pk_fma_f32 v[18:19], v[12:13], v[170:171], v[18:19]
	v_pk_fma_f32 v[36:37], v[14:15], v[176:177], v[36:37]
	v_pk_fma_f32 v[20:21], v[12:13], v[174:175], v[20:21]
	v_pk_fma_f32 v[38:39], v[14:15], v[180:181], v[38:39]
	v_pk_fma_f32 v[22:23], v[12:13], v[178:179], v[22:23]
	v_pk_fma_f32 v[40:41], v[14:15], v[184:185], v[40:41]
	v_pk_fma_f32 v[24:25], v[12:13], v[182:183], v[24:25]
	v_pk_fma_f32 v[42:43], v[14:15], v[188:189], v[42:43]
	v_pk_fma_f32 v[26:27], v[12:13], v[186:187], v[26:27]
	ds_read_b128 v[12:15], v218 offset:13312
	s_waitcnt lgkmcnt(0)
	v_pk_fma_f32 v[44:45], v[12:13], v[162:163], v[44:45]
	v_pk_fma_f32 v[28:29], v[14:15], v[164:165], v[28:29]
	v_pk_fma_f32 v[46:47], v[12:13], v[166:167], v[46:47]
	v_pk_fma_f32 v[30:31], v[14:15], v[168:169], v[30:31]
	v_pk_fma_f32 v[16:17], v[12:13], v[170:171], v[16:17]
	v_pk_fma_f32 v[32:33], v[14:15], v[172:173], v[32:33]
	v_pk_fma_f32 v[18:19], v[12:13], v[174:175], v[18:19]
	v_pk_fma_f32 v[34:35], v[14:15], v[176:177], v[34:35]
	v_pk_fma_f32 v[20:21], v[12:13], v[178:179], v[20:21]
	v_pk_fma_f32 v[36:37], v[14:15], v[180:181], v[36:37]
	v_pk_fma_f32 v[22:23], v[12:13], v[182:183], v[22:23]
	v_pk_fma_f32 v[38:39], v[14:15], v[184:185], v[38:39]
	v_pk_fma_f32 v[24:25], v[12:13], v[186:187], v[24:25]
	v_pk_fma_f32 v[40:41], v[14:15], v[188:189], v[40:41]
	v_pk_fma_f32 v[26:27], v[12:13], v[190:191], v[26:27]
	v_pk_fma_f32 v[42:43], v[14:15], v[192:193], v[42:43]
	ds_read_b128 v[12:15], v218 offset:14336
	s_waitcnt lgkmcnt(0)
	v_pk_fma_f32 v[28:29], v[14:15], v[168:169], v[28:29]
	v_pk_fma_f32 v[44:45], v[12:13], v[166:167], v[44:45]
	v_pk_fma_f32 v[30:31], v[14:15], v[172:173], v[30:31]
	v_pk_fma_f32 v[46:47], v[12:13], v[170:171], v[46:47]
	v_pk_fma_f32 v[48:49], v[14:15], v[176:177], v[32:33]
	v_pk_fma_f32 v[50:51], v[12:13], v[174:175], v[16:17]
	v_pk_fma_f32 v[52:53], v[14:15], v[180:181], v[34:35]
	v_pk_fma_f32 v[54:55], v[12:13], v[178:179], v[18:19]
	v_pk_fma_f32 v[56:57], v[14:15], v[184:185], v[36:37]
	v_pk_fma_f32 v[58:59], v[12:13], v[182:183], v[20:21]
	v_pk_fma_f32 v[60:61], v[14:15], v[188:189], v[38:39]
	v_pk_fma_f32 v[62:63], v[12:13], v[186:187], v[22:23]
	v_pk_fma_f32 v[64:65], v[14:15], v[192:193], v[40:41]
	v_pk_fma_f32 v[66:67], v[12:13], v[190:191], v[24:25]
	v_pk_fma_f32 v[162:163], v[14:15], v[200:201], v[42:43]
	v_pk_fma_f32 v[164:165], v[12:13], v[198:199], v[26:27]
	ds_read_b128 v[12:15], v218 offset:15360
	s_waitcnt lgkmcnt(0)
	v_pk_fma_f32 v[16:17], v[12:13], v[170:171], v[44:45]
	v_pk_fma_f32 v[32:33], v[14:15], v[172:173], v[28:29]
	v_pk_fma_f32 v[18:19], v[12:13], v[174:175], v[46:47]
	v_pk_fma_f32 v[34:35], v[14:15], v[176:177], v[30:31]
	v_pk_fma_f32 v[20:21], v[12:13], v[178:179], v[50:51]
	v_pk_fma_f32 v[22:23], v[12:13], v[182:183], v[54:55]
	v_pk_fma_f32 v[24:25], v[12:13], v[186:187], v[58:59]
	v_pk_fma_f32 v[26:27], v[12:13], v[190:191], v[62:63]
	v_pk_fma_f32 v[28:29], v[12:13], v[198:199], v[66:67]
	v_pk_fma_f32 v[30:31], v[12:13], v[204:205], v[164:165]
	v_or_b32_e32 v12, s16, v223
	v_lshl_add_u32 v166, v12, 9, v217
	v_pk_fma_f32 v[36:37], v[14:15], v[180:181], v[48:49]
	v_pk_fma_f32 v[38:39], v[14:15], v[184:185], v[52:53]
	v_pk_fma_f32 v[40:41], v[14:15], v[188:189], v[56:57]
	v_pk_fma_f32 v[42:43], v[14:15], v[192:193], v[60:61]
	v_pk_fma_f32 v[44:45], v[14:15], v[200:201], v[64:65]
	v_pk_fma_f32 v[46:47], v[14:15], v[206:207], v[162:163]
	ds_read2st64_b64 v[12:15], v166 offset1:1
	s_waitcnt lgkmcnt(0)
	v_lshlrev_b32_e32 v56, 16, v12
	v_and_b32_e32 v57, 0xffff0000, v12
	v_lshlrev_b32_e32 v58, 16, v13
	v_and_b32_e32 v59, 0xffff0000, v13
	v_lshlrev_b32_e32 v48, 16, v14
	v_and_b32_e32 v49, 0xffff0000, v14
	v_lshlrev_b32_e32 v50, 16, v15
	v_and_b32_e32 v51, 0xffff0000, v15
	ds_read2st64_b64 v[12:15], v166 offset0:2 offset1:3
	s_waitcnt lgkmcnt(0)
	v_lshlrev_b32_e32 v60, 16, v12
	v_and_b32_e32 v61, 0xffff0000, v12
	v_lshlrev_b32_e32 v62, 16, v13
	v_and_b32_e32 v63, 0xffff0000, v13
	v_lshlrev_b32_e32 v52, 16, v14
	v_and_b32_e32 v53, 0xffff0000, v14
	v_lshlrev_b32_e32 v54, 16, v15
	v_and_b32_e32 v55, 0xffff0000, v15
	ds_read2st64_b64 v[12:15], v166 offset0:4 offset1:5
	s_waitcnt lgkmcnt(0)
	v_lshlrev_b32_e32 v162, 16, v12
	v_and_b32_e32 v163, 0xffff0000, v12
	v_lshlrev_b32_e32 v164, 16, v13
	v_and_b32_e32 v165, 0xffff0000, v13
	v_lshlrev_b32_e32 v64, 16, v14
	v_and_b32_e32 v65, 0xffff0000, v14
	v_lshlrev_b32_e32 v66, 16, v15
	v_and_b32_e32 v67, 0xffff0000, v15
	ds_read2st64_b64 v[12:15], v166 offset0:6 offset1:7
	s_waitcnt lgkmcnt(0)
	v_lshlrev_b32_e32 v168, 16, v12
	v_and_b32_e32 v169, 0xffff0000, v12
	v_lshlrev_b32_e32 v170, 16, v13
	v_and_b32_e32 v171, 0xffff0000, v13
	v_lshlrev_b32_e32 v172, 16, v14
	v_and_b32_e32 v173, 0xffff0000, v14
	v_lshlrev_b32_e32 v174, 16, v15
	v_and_b32_e32 v175, 0xffff0000, v15
	ds_read2st64_b64 v[12:15], v166 offset0:8 offset1:9
	s_waitcnt lgkmcnt(0)
	v_lshlrev_b32_e32 v176, 16, v12
	v_and_b32_e32 v177, 0xffff0000, v12
	v_lshlrev_b32_e32 v178, 16, v13
	v_and_b32_e32 v179, 0xffff0000, v13
	v_lshlrev_b32_e32 v180, 16, v14
	v_and_b32_e32 v181, 0xffff0000, v14
	v_lshlrev_b32_e32 v182, 16, v15
	v_and_b32_e32 v183, 0xffff0000, v15
	ds_read2st64_b64 v[12:15], v166 offset0:10 offset1:11
	s_waitcnt lgkmcnt(0)
; #define LAS __attribute__((address_space(3)))
; __device__ __forceinline__ float bflo(unsigned w) { return __uint_as_float(w << 16); }
; __device__ __forceinline__ float bfhi(unsigned w) { return __uint_as_float(w & 0xffff0000u); }
; __device__ __forceinline__ void phase_branch(const KP2& p, int l, LAS unsigned char* lds) {
;     ...
;                     for (int kc = 0; kc < 4; ++kc) {
;                         asm volatile("" ::: "memory");
;                         f32x4 x[15];
; #pragma unroll
;                         for (int rr = 0; rr < 15; ++rr) if (kc < 3 || rr < 14) { const u32x2 v = *(const LAS u32x2*)(tile + (tb + 8 * kc + rr) * 512 + lane * 8); x[rr] = (f32x4){bflo(v.x), bfhi(v.x), bflo(v.y), bfhi(v.y)}; }
; #pragma unroll
;                         for (int kk = 0; kk < 8; ++kk) if (8 * kc + kk < 31) { const f32x4 wk = ((const LAS f32x4*)wl)[(8 * kc + kk) * 64 + lane];
; #pragma unroll
;                             for (int t = 0; t < 8; ++t) acc[t] += wk * x[t + kk]; }
	v_lshlrev_b32_e32 v184, 16, v12
	v_and_b32_e32 v185, 0xffff0000, v12
	v_lshlrev_b32_e32 v186, 16, v13
	v_and_b32_e32 v187, 0xffff0000, v13
	v_lshlrev_b32_e32 v188, 16, v14
	v_and_b32_e32 v189, 0xffff0000, v14
	v_lshlrev_b32_e32 v190, 16, v15
	v_and_b32_e32 v191, 0xffff0000, v15
	ds_read2st64_b64 v[12:15], v166 offset0:12 offset1:13
	s_waitcnt lgkmcnt(0)
	v_lshlrev_b32_e32 v192, 16, v12
	v_and_b32_e32 v193, 0xffff0000, v12
	v_lshlrev_b32_e32 v198, 16, v13
	v_and_b32_e32 v199, 0xffff0000, v13
	ds_read_b64 v[12:13], v166 offset:7168
	v_lshlrev_b32_e32 v200, 16, v14
	v_and_b32_e32 v201, 0xffff0000, v14
	v_lshlrev_b32_e32 v204, 16, v15
	v_and_b32_e32 v205, 0xffff0000, v15
	s_waitcnt lgkmcnt(0)
	v_lshlrev_b32_e32 v166, 16, v12
	v_and_b32_e32 v167, 0xffff0000, v12
	v_lshlrev_b32_e32 v206, 16, v13
	v_and_b32_e32 v207, 0xffff0000, v13
	ds_read_b128 v[12:15], v218 offset:16384
	s_waitcnt lgkmcnt(0)
	v_pk_fma_f32 v[32:33], v[14:15], v[58:59], v[32:33]
	v_pk_fma_f32 v[16:17], v[12:13], v[56:57], v[16:17]
	v_pk_fma_f32 v[34:35], v[14:15], v[50:51], v[34:35]
	v_pk_fma_f32 v[18:19], v[12:13], v[48:49], v[18:19]
	v_pk_fma_f32 v[36:37], v[14:15], v[62:63], v[36:37]
	v_pk_fma_f32 v[20:21], v[12:13], v[60:61], v[20:21]
	v_pk_fma_f32 v[38:39], v[14:15], v[54:55], v[38:39]
	v_pk_fma_f32 v[22:23], v[12:13], v[52:53], v[22:23]
	v_pk_fma_f32 v[40:41], v[14:15], v[164:165], v[40:41]
	v_pk_fma_f32 v[24:25], v[12:13], v[162:163], v[24:25]
	v_pk_fma_f32 v[42:43], v[14:15], v[66:67], v[42:43]
	v_pk_fma_f32 v[26:27], v[12:13], v[64:65], v[26:27]
	v_pk_fma_f32 v[44:45], v[14:15], v[170:171], v[44:45]
	v_pk_fma_f32 v[28:29], v[12:13], v[168:169], v[28:29]
	v_pk_fma_f32 v[46:47], v[14:15], v[174:175], v[46:47]
	v_pk_fma_f32 v[30:31], v[12:13], v[172:173], v[30:31]
	ds_read_b128 v[12:15], v218 offset:17408
	s_waitcnt lgkmcnt(0)
	v_pk_fma_f32 v[16:17], v[12:13], v[48:49], v[16:17]
	v_pk_fma_f32 v[32:33], v[14:15], v[50:51], v[32:33]
	v_pk_fma_f32 v[18:19], v[12:13], v[60:61], v[18:19]
	v_pk_fma_f32 v[34:35], v[14:15], v[62:63], v[34:35]
	v_pk_fma_f32 v[20:21], v[12:13], v[52:53], v[20:21]
	v_pk_fma_f32 v[36:37], v[14:15], v[54:55], v[36:37]
	v_pk_fma_f32 v[22:23], v[12:13], v[162:163], v[22:23]
	v_pk_fma_f32 v[38:39], v[14:15], v[164:165], v[38:39]
	v_pk_fma_f32 v[24:25], v[12:13], v[64:65], v[24:25]
	v_pk_fma_f32 v[40:41], v[14:15], v[66:67], v[40:41]
	v_pk_fma_f32 v[26:27], v[12:13], v[168:169], v[26:27]
	v_pk_fma_f32 v[42:43], v[14:15], v[170:171], v[42:43]
	v_pk_fma_f32 v[28:29], v[12:13], v[172:173], v[28:29]
	v_pk_fma_f32 v[44:45], v[14:15], v[174:175], v[44:45]
	v_pk_fma_f32 v[30:31], v[12:13], v[176:177], v[30:31]
	v_pk_fma_f32 v[46:47], v[14:15], v[178:179], v[46:47]
	ds_read_b128 v[12:15], v218 offset:18432
	s_waitcnt lgkmcnt(0)
	v_pk_fma_f32 v[32:33], v[14:15], v[62:63], v[32:33]
	v_pk_fma_f32 v[16:17], v[12:13], v[60:61], v[16:17]
	v_pk_fma_f32 v[34:35], v[14:15], v[54:55], v[34:35]
	v_pk_fma_f32 v[18:19], v[12:13], v[52:53], v[18:19]
	v_pk_fma_f32 v[36:37], v[14:15], v[164:165], v[36:37]
	v_pk_fma_f32 v[20:21], v[12:13], v[162:163], v[20:21]
	v_pk_fma_f32 v[38:39], v[14:15], v[66:67], v[38:39]
	v_pk_fma_f32 v[22:23], v[12:13], v[64:65], v[22:23]
	v_pk_fma_f32 v[40:41], v[14:15], v[170:171], v[40:41]
	v_pk_fma_f32 v[24:25], v[12:13], v[168:169], v[24:25]
	v_pk_fma_f32 v[42:43], v[14:15], v[174:175], v[42:43]
	v_pk_fma_f32 v[26:27], v[12:13], v[172:173], v[26:27]
	v_pk_fma_f32 v[44:45], v[14:15], v[178:179], v[44:45]
	v_pk_fma_f32 v[28:29], v[12:13], v[176:177], v[28:29]
	v_pk_fma_f32 v[46:47], v[14:15], v[182:183], v[46:47]
	v_pk_fma_f32 v[30:31], v[12:13], v[180:181], v[30:31]
	ds_read_b128 v[12:15], v218 offset:19456
	s_waitcnt lgkmcnt(0)
	v_pk_fma_f32 v[16:17], v[12:13], v[52:53], v[16:17]
	v_pk_fma_f32 v[32:33], v[14:15], v[54:55], v[32:33]
	v_pk_fma_f32 v[18:19], v[12:13], v[162:163], v[18:19]
	v_pk_fma_f32 v[34:35], v[14:15], v[164:165], v[34:35]
	v_pk_fma_f32 v[20:21], v[12:13], v[64:65], v[20:21]
	v_pk_fma_f32 v[36:37], v[14:15], v[66:67], v[36:37]
	v_pk_fma_f32 v[22:23], v[12:13], v[168:169], v[22:23]
	v_pk_fma_f32 v[38:39], v[14:15], v[170:171], v[38:39]
	v_pk_fma_f32 v[24:25], v[12:13], v[172:173], v[24:25]
	v_pk_fma_f32 v[40:41], v[14:15], v[174:175], v[40:41]
	v_pk_fma_f32 v[26:27], v[12:13], v[176:177], v[26:27]
	v_pk_fma_f32 v[42:43], v[14:15], v[178:179], v[42:43]
	v_pk_fma_f32 v[28:29], v[12:13], v[180:181], v[28:29]
	v_pk_fma_f32 v[44:45], v[14:15], v[182:183], v[44:45]
	v_pk_fma_f32 v[30:31], v[12:13], v[184:185], v[30:31]
	v_pk_fma_f32 v[46:47], v[14:15], v[186:187], v[46:47]
	ds_read_b128 v[12:15], v218 offset:20480
	s_waitcnt lgkmcnt(0)
	v_pk_fma_f32 v[32:33], v[14:15], v[164:165], v[32:33]
	v_pk_fma_f32 v[16:17], v[12:13], v[162:163], v[16:17]
	v_pk_fma_f32 v[34:35], v[14:15], v[66:67], v[34:35]
	v_pk_fma_f32 v[18:19], v[12:13], v[64:65], v[18:19]
	v_pk_fma_f32 v[36:37], v[14:15], v[170:171], v[36:37]
	v_pk_fma_f32 v[20:21], v[12:13], v[168:169], v[20:21]
	v_pk_fma_f32 v[38:39], v[14:15], v[174:175], v[38:39]
	v_pk_fma_f32 v[22:23], v[12:13], v[172:173], v[22:23]
	v_pk_fma_f32 v[40:41], v[14:15], v[178:179], v[40:41]
	v_pk_fma_f32 v[24:25], v[12:13], v[176:177], v[24:25]
	v_pk_fma_f32 v[42:43], v[14:15], v[182:183], v[42:43]
	v_pk_fma_f32 v[26:27], v[12:13], v[180:181], v[26:27]
	v_pk_fma_f32 v[44:45], v[14:15], v[186:187], v[44:45]
	v_pk_fma_f32 v[28:29], v[12:13], v[184:185], v[28:29]
	v_pk_fma_f32 v[46:47], v[14:15], v[190:191], v[46:47]
	v_pk_fma_f32 v[30:31], v[12:13], v[188:189], v[30:31]
	ds_read_b128 v[12:15], v218 offset:21504
	s_waitcnt lgkmcnt(0)
; #define LAS __attribute__((address_space(3)))
; __device__ __forceinline__ float bflo(unsigned w) { return __uint_as_float(w << 16); }
; __device__ __forceinline__ float bfhi(unsigned w) { return __uint_as_float(w & 0xffff0000u); }
; __device__ __forceinline__ void phase_branch(const KP2& p, int l, LAS unsigned char* lds) {
;     ...
;                     for (int kc = 0; kc < 4; ++kc) {
;                         asm volatile("" ::: "memory");
;                         f32x4 x[15];
; #pragma unroll
;                         for (int rr = 0; rr < 15; ++rr) if (kc < 3 || rr < 14) { const u32x2 v = *(const LAS u32x2*)(tile + (tb + 8 * kc + rr) * 512 + lane * 8); x[rr] = (f32x4){bflo(v.x), bfhi(v.x), bflo(v.y), bfhi(v.y)}; }
; #pragma unroll
;                         for (int kk = 0; kk < 8; ++kk) if (8 * kc + kk < 31) { const f32x4 wk = ((const LAS f32x4*)wl)[(8 * kc + kk) * 64 + lane];
; #pragma unroll
;                             for (int t = 0; t < 8; ++t) acc[t] += wk * x[t + kk]; }
	v_pk_fma_f32 v[16:17], v[12:13], v[64:65], v[16:17]
	v_pk_fma_f32 v[32:33], v[14:15], v[66:67], v[32:33]
	v_pk_fma_f32 v[18:19], v[12:13], v[168:169], v[18:19]
	v_pk_fma_f32 v[34:35], v[14:15], v[170:171], v[34:35]
	v_pk_fma_f32 v[20:21], v[12:13], v[172:173], v[20:21]
	v_pk_fma_f32 v[36:37], v[14:15], v[174:175], v[36:37]
	v_pk_fma_f32 v[22:23], v[12:13], v[176:177], v[22:23]
	v_pk_fma_f32 v[38:39], v[14:15], v[178:179], v[38:39]
	v_pk_fma_f32 v[24:25], v[12:13], v[180:181], v[24:25]
	v_pk_fma_f32 v[40:41], v[14:15], v[182:183], v[40:41]
	v_pk_fma_f32 v[26:27], v[12:13], v[184:185], v[26:27]
	v_pk_fma_f32 v[42:43], v[14:15], v[186:187], v[42:43]
	v_pk_fma_f32 v[28:29], v[12:13], v[188:189], v[28:29]
	v_pk_fma_f32 v[44:45], v[14:15], v[190:191], v[44:45]
	v_pk_fma_f32 v[30:31], v[12:13], v[192:193], v[30:31]
	v_pk_fma_f32 v[46:47], v[14:15], v[198:199], v[46:47]
	ds_read_b128 v[12:15], v218 offset:22528
	s_waitcnt lgkmcnt(0)
	v_pk_fma_f32 v[48:49], v[14:15], v[190:191], v[42:43]
	v_pk_fma_f32 v[50:51], v[14:15], v[198:199], v[44:45]
	ds_read_b128 v[42:45], v218 offset:23552
	v_pk_fma_f32 v[32:33], v[14:15], v[170:171], v[32:33]
	v_pk_fma_f32 v[16:17], v[12:13], v[168:169], v[16:17]
	v_pk_fma_f32 v[34:35], v[14:15], v[174:175], v[34:35]
	v_pk_fma_f32 v[18:19], v[12:13], v[172:173], v[18:19]
	v_pk_fma_f32 v[36:37], v[14:15], v[178:179], v[36:37]
	v_pk_fma_f32 v[20:21], v[12:13], v[176:177], v[20:21]
	v_pk_fma_f32 v[38:39], v[14:15], v[182:183], v[38:39]
	v_pk_fma_f32 v[22:23], v[12:13], v[180:181], v[22:23]
	v_pk_fma_f32 v[40:41], v[14:15], v[186:187], v[40:41]
	v_pk_fma_f32 v[24:25], v[12:13], v[184:185], v[24:25]
	v_pk_fma_f32 v[26:27], v[12:13], v[188:189], v[26:27]
	v_pk_fma_f32 v[52:53], v[12:13], v[192:193], v[28:29]
	v_pk_fma_f32 v[46:47], v[14:15], v[204:205], v[46:47]
	v_pk_fma_f32 v[54:55], v[12:13], v[200:201], v[30:31]
	s_waitcnt lgkmcnt(0)
	v_pk_fma_f32 v[12:13], v[42:43], v[172:173], v[16:17]
	v_pk_fma_f32 v[28:29], v[44:45], v[174:175], v[32:33]
	v_pk_fma_f32 v[14:15], v[42:43], v[176:177], v[18:19]
	v_pk_fma_f32 v[30:31], v[44:45], v[178:179], v[34:35]
	v_pk_fma_f32 v[16:17], v[42:43], v[180:181], v[20:21]
	v_pk_fma_f32 v[32:33], v[44:45], v[182:183], v[36:37]
	v_pk_fma_f32 v[18:19], v[42:43], v[184:185], v[22:23]
	v_pk_fma_f32 v[34:35], v[44:45], v[186:187], v[38:39]
	v_pk_fma_f32 v[20:21], v[42:43], v[188:189], v[24:25]
	v_pk_fma_f32 v[36:37], v[44:45], v[190:191], v[40:41]
	v_pk_fma_f32 v[22:23], v[42:43], v[192:193], v[26:27]
	v_pk_fma_f32 v[38:39], v[44:45], v[198:199], v[48:49]
	v_pk_fma_f32 v[24:25], v[42:43], v[200:201], v[52:53]
	v_pk_fma_f32 v[40:41], v[44:45], v[204:205], v[50:51]
	v_pk_fma_f32 v[26:27], v[42:43], v[166:167], v[54:55]
	v_pk_fma_f32 v[42:43], v[44:45], v[206:207], v[46:47]
	v_add_u32_e32 v44, s16, v224
	v_lshl_add_u32 v50, v44, 9, v217
	ds_read2st64_b64 v[44:47], v50 offset1:1
	ds_read2st64_b64 v[52:55], v50 offset0:2 offset1:3
	s_mov_b32 s16, 8
	s_waitcnt lgkmcnt(1)
	v_lshlrev_b32_e32 v48, 16, v44
	s_waitcnt lgkmcnt(0)
	v_lshlrev_b32_e32 v58, 16, v52
	v_and_b32_e32 v59, 0xffff0000, v52
	v_lshlrev_b32_e32 v60, 16, v53
	v_and_b32_e32 v61, 0xffff0000, v53
	v_lshlrev_b32_e32 v62, 16, v54
	v_and_b32_e32 v63, 0xffff0000, v54
	v_lshlrev_b32_e32 v64, 16, v55
	v_and_b32_e32 v65, 0xffff0000, v55
	ds_read2st64_b64 v[52:55], v50 offset0:4 offset1:5
	v_and_b32_e32 v49, 0xffff0000, v44
	v_lshlrev_b32_e32 v56, 16, v45
	v_and_b32_e32 v57, 0xffff0000, v45
	v_lshlrev_b32_e32 v44, 16, v46
	s_waitcnt lgkmcnt(0)
	v_lshlrev_b32_e32 v66, 16, v52
	v_and_b32_e32 v67, 0xffff0000, v52
	v_lshlrev_b32_e32 v162, 16, v53
	v_and_b32_e32 v163, 0xffff0000, v53
	v_lshlrev_b32_e32 v164, 16, v54
	v_and_b32_e32 v165, 0xffff0000, v54
	v_lshlrev_b32_e32 v166, 16, v55
	v_and_b32_e32 v167, 0xffff0000, v55
	ds_read2st64_b64 v[52:55], v50 offset0:6 offset1:7
	v_and_b32_e32 v45, 0xffff0000, v46
	v_lshlrev_b32_e32 v46, 16, v47
	v_and_b32_e32 v47, 0xffff0000, v47
	s_waitcnt lgkmcnt(0)
	v_lshlrev_b32_e32 v168, 16, v52
	v_and_b32_e32 v169, 0xffff0000, v52
	v_lshlrev_b32_e32 v170, 16, v53
	v_and_b32_e32 v171, 0xffff0000, v53
	v_lshlrev_b32_e32 v172, 16, v54
	v_and_b32_e32 v173, 0xffff0000, v54
	v_lshlrev_b32_e32 v174, 16, v55
	v_and_b32_e32 v175, 0xffff0000, v55
	ds_read2st64_b64 v[52:55], v50 offset0:8 offset1:9
	s_waitcnt lgkmcnt(0)
	v_lshlrev_b32_e32 v176, 16, v52
	v_and_b32_e32 v177, 0xffff0000, v52
	v_lshlrev_b32_e32 v178, 16, v53
	v_and_b32_e32 v179, 0xffff0000, v53
	v_lshlrev_b32_e32 v180, 16, v54
	v_and_b32_e32 v181, 0xffff0000, v54
	v_lshlrev_b32_e32 v182, 16, v55
	v_and_b32_e32 v183, 0xffff0000, v55
	ds_read2st64_b64 v[52:55], v50 offset0:10 offset1:11
	s_waitcnt lgkmcnt(0)
	v_lshlrev_b32_e32 v184, 16, v52
	v_and_b32_e32 v185, 0xffff0000, v52
	v_lshlrev_b32_e32 v186, 16, v53
	v_and_b32_e32 v187, 0xffff0000, v53
	ds_read2st64_b64 v[50:53], v50 offset0:12 offset1:13
	v_lshlrev_b32_e32 v188, 16, v54
	v_and_b32_e32 v189, 0xffff0000, v54
	v_lshlrev_b32_e32 v54, 16, v55
	v_and_b32_e32 v55, 0xffff0000, v55
	s_waitcnt lgkmcnt(0)
	v_lshlrev_b32_e32 v190, 16, v50
	v_and_b32_e32 v191, 0xffff0000, v50
	v_lshlrev_b32_e32 v192, 16, v51
	v_and_b32_e32 v193, 0xffff0000, v51
	v_lshlrev_b32_e32 v198, 16, v52
	v_and_b32_e32 v199, 0xffff0000, v52
	v_lshlrev_b32_e32 v200, 16, v53
	v_and_b32_e32 v201, 0xffff0000, v53
	ds_read_b128 v[50:53], v218 offset:24576
	s_waitcnt lgkmcnt(0)
; #define LAS __attribute__((address_space(3)))
; __device__ __forceinline__ float bflo(unsigned w) { return __uint_as_float(w << 16); }
; __device__ __forceinline__ float bfhi(unsigned w) { return __uint_as_float(w & 0xffff0000u); }
; __device__ __forceinline__ void phase_branch(const KP2& p, int l, LAS unsigned char* lds) {
;     ...
;                     for (int kc = 0; kc < 4; ++kc) {
;                         asm volatile("" ::: "memory");
;                         f32x4 x[15];
; #pragma unroll
;                         for (int rr = 0; rr < 15; ++rr) if (kc < 3 || rr < 14) { const u32x2 v = *(const LAS u32x2*)(tile + (tb + 8 * kc + rr) * 512 + lane * 8); x[rr] = (f32x4){bflo(v.x), bfhi(v.x), bflo(v.y), bfhi(v.y)}; }
; #pragma unroll
;                         for (int kk = 0; kk < 8; ++kk) if (8 * kc + kk < 31) { const f32x4 wk = ((const LAS f32x4*)wl)[(8 * kc + kk) * 64 + lane];
; #pragma unroll
;                             for (int t = 0; t < 8; ++t) acc[t] += wk * x[t + kk]; }
	v_pk_fma_f32 v[28:29], v[52:53], v[56:57], v[28:29]
	v_pk_fma_f32 v[48:49], v[50:51], v[48:49], v[12:13]
	v_pk_fma_f32 v[56:57], v[50:51], v[44:45], v[14:15]
	ds_read_b128 v[12:15], v218 offset:25600
	v_pk_fma_f32 v[30:31], v[52:53], v[46:47], v[30:31]
	v_pk_fma_f32 v[32:33], v[52:53], v[60:61], v[32:33]
	v_pk_fma_f32 v[16:17], v[50:51], v[58:59], v[16:17]
	v_pk_fma_f32 v[34:35], v[52:53], v[64:65], v[34:35]
	v_pk_fma_f32 v[18:19], v[50:51], v[62:63], v[18:19]
	v_pk_fma_f32 v[36:37], v[52:53], v[162:163], v[36:37]
	v_pk_fma_f32 v[20:21], v[50:51], v[66:67], v[20:21]
	v_pk_fma_f32 v[38:39], v[52:53], v[166:167], v[38:39]
	v_pk_fma_f32 v[22:23], v[50:51], v[164:165], v[22:23]
	v_pk_fma_f32 v[40:41], v[52:53], v[170:171], v[40:41]
	v_pk_fma_f32 v[24:25], v[50:51], v[168:169], v[24:25]
	v_pk_fma_f32 v[42:43], v[52:53], v[174:175], v[42:43]
	v_pk_fma_f32 v[26:27], v[50:51], v[172:173], v[26:27]
	s_waitcnt lgkmcnt(0)
	v_pk_fma_f32 v[44:45], v[12:13], v[44:45], v[48:49]
	v_pk_fma_f32 v[28:29], v[14:15], v[46:47], v[28:29]
	v_pk_fma_f32 v[46:47], v[12:13], v[58:59], v[56:57]
	v_pk_fma_f32 v[30:31], v[14:15], v[60:61], v[30:31]
	v_pk_fma_f32 v[16:17], v[12:13], v[62:63], v[16:17]
	v_pk_fma_f32 v[32:33], v[14:15], v[64:65], v[32:33]
	v_pk_fma_f32 v[18:19], v[12:13], v[66:67], v[18:19]
	v_pk_fma_f32 v[34:35], v[14:15], v[162:163], v[34:35]
	v_pk_fma_f32 v[20:21], v[12:13], v[164:165], v[20:21]
	v_pk_fma_f32 v[36:37], v[14:15], v[166:167], v[36:37]
	v_pk_fma_f32 v[22:23], v[12:13], v[168:169], v[22:23]
	v_pk_fma_f32 v[38:39], v[14:15], v[170:171], v[38:39]
	v_pk_fma_f32 v[24:25], v[12:13], v[172:173], v[24:25]
	v_pk_fma_f32 v[40:41], v[14:15], v[174:175], v[40:41]
	v_pk_fma_f32 v[26:27], v[12:13], v[176:177], v[26:27]
	v_pk_fma_f32 v[42:43], v[14:15], v[178:179], v[42:43]
	ds_read_b128 v[12:15], v218 offset:26624
	s_waitcnt lgkmcnt(0)
	v_pk_fma_f32 v[28:29], v[14:15], v[60:61], v[28:29]
	v_pk_fma_f32 v[44:45], v[12:13], v[58:59], v[44:45]
	v_pk_fma_f32 v[30:31], v[14:15], v[64:65], v[30:31]
	v_pk_fma_f32 v[46:47], v[12:13], v[62:63], v[46:47]
	v_pk_fma_f32 v[32:33], v[14:15], v[162:163], v[32:33]
	v_pk_fma_f32 v[16:17], v[12:13], v[66:67], v[16:17]
	v_pk_fma_f32 v[34:35], v[14:15], v[166:167], v[34:35]
	v_pk_fma_f32 v[18:19], v[12:13], v[164:165], v[18:19]
	v_pk_fma_f32 v[36:37], v[14:15], v[170:171], v[36:37]
	v_pk_fma_f32 v[20:21], v[12:13], v[168:169], v[20:21]
	v_pk_fma_f32 v[38:39], v[14:15], v[174:175], v[38:39]
	v_pk_fma_f32 v[22:23], v[12:13], v[172:173], v[22:23]
	v_pk_fma_f32 v[40:41], v[14:15], v[178:179], v[40:41]
	v_pk_fma_f32 v[24:25], v[12:13], v[176:177], v[24:25]
	v_pk_fma_f32 v[42:43], v[14:15], v[182:183], v[42:43]
	v_pk_fma_f32 v[26:27], v[12:13], v[180:181], v[26:27]
	ds_read_b128 v[12:15], v218 offset:27648
	s_waitcnt lgkmcnt(0)
	v_pk_fma_f32 v[44:45], v[12:13], v[62:63], v[44:45]
	v_pk_fma_f32 v[28:29], v[14:15], v[64:65], v[28:29]
	v_pk_fma_f32 v[46:47], v[12:13], v[66:67], v[46:47]
	v_pk_fma_f32 v[30:31], v[14:15], v[162:163], v[30:31]
	v_pk_fma_f32 v[16:17], v[12:13], v[164:165], v[16:17]
	v_pk_fma_f32 v[32:33], v[14:15], v[166:167], v[32:33]
	v_pk_fma_f32 v[18:19], v[12:13], v[168:169], v[18:19]
	v_pk_fma_f32 v[34:35], v[14:15], v[170:171], v[34:35]
	v_pk_fma_f32 v[20:21], v[12:13], v[172:173], v[20:21]
	v_pk_fma_f32 v[36:37], v[14:15], v[174:175], v[36:37]
	v_pk_fma_f32 v[22:23], v[12:13], v[176:177], v[22:23]
	v_pk_fma_f32 v[38:39], v[14:15], v[178:179], v[38:39]
	v_pk_fma_f32 v[24:25], v[12:13], v[180:181], v[24:25]
	v_pk_fma_f32 v[40:41], v[14:15], v[182:183], v[40:41]
	v_pk_fma_f32 v[26:27], v[12:13], v[184:185], v[26:27]
	v_pk_fma_f32 v[42:43], v[14:15], v[186:187], v[42:43]
	ds_read_b128 v[12:15], v218 offset:28672
	s_waitcnt lgkmcnt(0)
	v_pk_fma_f32 v[28:29], v[14:15], v[162:163], v[28:29]
	v_pk_fma_f32 v[44:45], v[12:13], v[66:67], v[44:45]
	v_pk_fma_f32 v[30:31], v[14:15], v[166:167], v[30:31]
	v_pk_fma_f32 v[46:47], v[12:13], v[164:165], v[46:47]
	v_pk_fma_f32 v[32:33], v[14:15], v[170:171], v[32:33]
	v_pk_fma_f32 v[16:17], v[12:13], v[168:169], v[16:17]
	v_pk_fma_f32 v[34:35], v[14:15], v[174:175], v[34:35]
	v_pk_fma_f32 v[18:19], v[12:13], v[172:173], v[18:19]
	v_pk_fma_f32 v[36:37], v[14:15], v[178:179], v[36:37]
	v_pk_fma_f32 v[20:21], v[12:13], v[176:177], v[20:21]
	v_pk_fma_f32 v[38:39], v[14:15], v[182:183], v[38:39]
	v_pk_fma_f32 v[22:23], v[12:13], v[180:181], v[22:23]
	v_pk_fma_f32 v[40:41], v[14:15], v[186:187], v[40:41]
	v_pk_fma_f32 v[24:25], v[12:13], v[184:185], v[24:25]
	v_pk_fma_f32 v[42:43], v[14:15], v[54:55], v[42:43]
	v_pk_fma_f32 v[26:27], v[12:13], v[188:189], v[26:27]
	ds_read_b128 v[12:15], v218 offset:29696
	s_waitcnt lgkmcnt(0)
	v_pk_fma_f32 v[48:49], v[12:13], v[164:165], v[44:45]
	v_pk_fma_f32 v[50:51], v[12:13], v[168:169], v[46:47]
	ds_read_b128 v[44:47], v218 offset:30720
	v_pk_fma_f32 v[30:31], v[14:15], v[170:171], v[30:31]
	v_pk_fma_f32 v[16:17], v[12:13], v[172:173], v[16:17]
	v_pk_fma_f32 v[18:19], v[12:13], v[176:177], v[18:19]
	v_pk_fma_f32 v[20:21], v[12:13], v[180:181], v[20:21]
	v_pk_fma_f32 v[22:23], v[12:13], v[184:185], v[22:23]
	v_pk_fma_f32 v[60:61], v[12:13], v[188:189], v[24:25]
	v_pk_fma_f32 v[64:65], v[12:13], v[190:191], v[26:27]
	v_pk_fma_f32 v[28:29], v[14:15], v[166:167], v[28:29]
	v_pk_fma_f32 v[32:33], v[14:15], v[174:175], v[32:33]
	v_pk_fma_f32 v[52:53], v[14:15], v[178:179], v[34:35]
	v_pk_fma_f32 v[56:57], v[14:15], v[182:183], v[36:37]
	v_pk_fma_f32 v[58:59], v[14:15], v[186:187], v[38:39]
	v_pk_fma_f32 v[62:63], v[14:15], v[54:55], v[40:41]
	v_pk_fma_f32 v[12:13], v[14:15], v[192:193], v[42:43]
	s_waitcnt lgkmcnt(0)
; #define LAS __attribute__((address_space(3)))
; __device__ __forceinline__ unsigned cvtpk(float lo, float hi) { unsigned r; asm("v_cvt_pk_bf16_f32 %0, %1, %2" : "=v"(r) : "v"(lo), "v"(hi)); return r; }
; __device__ __forceinline__ float sigm(float x) { return __builtin_amdgcn_rcpf(1.f + __expf(-x)); }
; __device__ __forceinline__ size_t oimg(int n, int row, int c) { return (size_t)((n * (MT / 128) + (row >> 7)) * 4 + (c >> 6)) * 8192 + (size_t)(pg8::lds_byte(row & 127, c & 63) >> 1); }
; __device__ __forceinline__ float wave_sum(float v) {
; #pragma unroll
;     for (int o = 1; o < 64; o <<= 1) v += __shfl_xor(v, o);
;     return v;
; }
; __device__ __forceinline__ void phase_branch(const KP2& p, int l, LAS unsigned char* lds) {
;     ...
;                         for (int kk = 0; kk < 8; ++kk) if (8 * kc + kk < 31) { const f32x4 wk = ((const LAS f32x4*)wl)[(8 * kc + kk) * 64 + lane];
; #pragma unroll
;                             for (int t = 0; t < 8; ++t) acc[t] += wk * x[t + kk]; }
;                     }
; #pragma unroll
;                     for (int t = 0; t < 8; ++t) {
;                         f32x4 v = acc[t]; const float mu = wave_sum((v.x + v.y) + (v.z + v.w)) * (1.f / BW);
;                         v = v - mu; const float rs = rsqrtf(wave_sum((v.x * v.x + v.y * v.y) + (v.z * v.z + v.w * v.w)) * (1.f / BW) + EPS);
;                         v = v * rs * lg + lb;
;                         u32x2 w; w.x = cvtpk(v.x * sigm(v.x), v.y * sigm(v.y)); w.y = cvtpk(v.z * sigm(v.z), v.w * sigm(v.w));
;                         *(u32x2*)(O + oimg(1, row0 + tb + t, 4 * lane)) = w;
	v_pk_fma_f32 v[42:43], v[44:45], v[168:169], v[48:49]
	v_pk_fma_f32 v[36:37], v[46:47], v[174:175], v[30:31]
	v_pk_fma_f32 v[38:39], v[44:45], v[172:173], v[50:51]
	v_pk_fma_f32 v[34:35], v[44:45], v[176:177], v[16:17]
	v_pk_fma_f32 v[30:31], v[44:45], v[180:181], v[18:19]
	v_pk_fma_f32 v[26:27], v[44:45], v[184:185], v[20:21]
	v_pk_fma_f32 v[22:23], v[44:45], v[188:189], v[22:23]
	v_pk_fma_f32 v[18:19], v[44:45], v[190:191], v[60:61]
	v_pk_fma_f32 v[14:15], v[44:45], v[198:199], v[64:65]
	v_and_b32_e32 v44, 64, v195
	v_pk_fma_f32 v[40:41], v[46:47], v[170:171], v[28:29]
	v_add_u32_e32 v49, 64, v44
	v_xor_b32_e32 v44, 1, v195
	v_pk_fma_f32 v[28:29], v[46:47], v[182:183], v[52:53]
	v_pk_fma_f32 v[20:21], v[46:47], v[54:55], v[58:59]
	v_cmp_lt_i32_e32 vcc, v44, v49
	v_pk_mov_b32 v[52:53], v[42:43], v[40:41] op_sel:[1,0]
	v_mov_b32_e32 v54, v42
	v_mov_b32_e32 v55, v41
	v_cndmask_b32_e32 v44, v195, v44, vcc
	v_pk_add_f32 v[52:53], v[52:53], v[54:55]
	v_lshlrev_b32_e32 v44, 2, v44
	v_add_f32_e32 v51, v52, v53
	ds_bpermute_b32 v52, v44, v51
	v_xor_b32_e32 v45, 2, v195
	v_cmp_lt_i32_e32 vcc, v45, v49
	v_pk_fma_f32 v[32:33], v[46:47], v[178:179], v[32:33]
	v_pk_fma_f32 v[24:25], v[46:47], v[186:187], v[56:57]
	v_cndmask_b32_e32 v45, v195, v45, vcc
	v_lshlrev_b32_e32 v45, 2, v45
	s_waitcnt lgkmcnt(0)
	v_add_f32_e32 v51, v51, v52
	ds_bpermute_b32 v52, v45, v51
	v_pk_fma_f32 v[16:17], v[46:47], v[192:193], v[62:63]
	v_pk_fma_f32 v[12:13], v[46:47], v[200:201], v[12:13]
	v_xor_b32_e32 v46, 4, v195
	v_cmp_lt_i32_e32 vcc, v46, v49
	s_waitcnt lgkmcnt(0)
	v_add_f32_e32 v51, v51, v52
	v_xor_b32_e32 v47, 8, v195
	v_cndmask_b32_e32 v46, v195, v46, vcc
	v_lshlrev_b32_e32 v46, 2, v46
	ds_bpermute_b32 v52, v46, v51
	v_cmp_lt_i32_e32 vcc, v47, v49
	v_xor_b32_e32 v48, 16, v195
	v_xor_b32_e32 v50, 32, v195
	v_cndmask_b32_e32 v47, v195, v47, vcc
	v_lshlrev_b32_e32 v47, 2, v47
	s_waitcnt lgkmcnt(0)
	v_add_f32_e32 v51, v51, v52
	ds_bpermute_b32 v52, v47, v51
	v_cmp_lt_i32_e32 vcc, v48, v49
	s_waitcnt lgkmcnt(0)
	v_add_f32_e32 v51, v51, v52
	v_cndmask_b32_e32 v48, v195, v48, vcc
	v_lshlrev_b32_e32 v48, 2, v48
	ds_bpermute_b32 v52, v48, v51
	v_cmp_lt_i32_e32 vcc, v50, v49
	s_waitcnt lgkmcnt(0)
	v_add_f32_e32 v51, v51, v52
	v_cndmask_b32_e32 v49, v195, v50, vcc
	v_lshlrev_b32_e32 v49, 2, v49
	ds_bpermute_b32 v52, v49, v51
	v_add_u32_e32 v50, s5, v144
	s_waitcnt lgkmcnt(0)
	v_add_f32_e32 v51, v51, v52
	v_fmamk_f32 v43, v51, 0xbb800000, v43
	v_fmac_f32_e32 v42, 0xbb800000, v51
	v_fmamk_f32 v41, v51, 0xbb800000, v41
	v_fmac_f32_e32 v40, 0xbb800000, v51
	v_pk_mul_f32 v[52:53], v[40:41], v[40:41]
	v_pk_mul_f32 v[54:55], v[42:43], v[42:43]
	s_nop 0
	v_pk_mov_b32 v[56:57], v[54:55], v[52:53] op_sel:[1,0]
	v_mov_b32_e32 v55, v53
	v_pk_add_f32 v[52:53], v[56:57], v[54:55]
	s_nop 0
	v_add_f32_e32 v51, v52, v53
	s_nop 1
	v_add_f32_dpp v51, v51, v51 quad_perm:[1,0,3,2] row_mask:0xf bank_mask:0xf
	s_nop 1
	v_add_f32_dpp v51, v51, v51 quad_perm:[2,3,0,1] row_mask:0xf bank_mask:0xf
	s_nop 1
	v_add_f32_dpp v51, v51, v51 row_half_mirror row_mask:0xf bank_mask:0xf
	s_nop 1
	v_add_f32_dpp v51, v51, v51 row_mirror row_mask:0xf bank_mask:0xf
	ds_bpermute_b32 v52, v48, v51
	s_waitcnt lgkmcnt(0)
	v_add_f32_e32 v51, v51, v52
	ds_bpermute_b32 v52, v49, v51
	s_waitcnt lgkmcnt(0)
	v_add_f32_e32 v51, v51, v52
	v_fmamk_f32 v51, v51, 0x3b800000, v196
	v_cmp_gt_f32_e32 vcc, s92, v51
	v_mul_f32_e32 v52, 0x4b800000, v51
	s_nop 0
	v_cndmask_b32_e32 v51, v51, v52, vcc
	v_rsq_f32_e32 v51, v51
	s_nop 0
	v_mul_f32_e32 v52, 0x45800000, v51
	v_cndmask_b32_e32 v52, v51, v52, vcc
	v_pk_mul_f32 v[42:43], v[42:43], v[52:53] op_sel_hi:[1,0]
	v_pk_mul_f32 v[40:41], v[40:41], v[52:53] op_sel_hi:[1,0]
	v_lshrrev_b32_e32 v51, 3, v50
	v_pk_fma_f32 v[52:53], v[6:7], v[40:41], v[10:11]
	v_pk_fma_f32 v[40:41], v[4:5], v[42:43], v[8:9]
	v_and_or_b32 v51, v51, 14, v220
	v_mul_f32_e32 v42, 0xbfb8aa3b, v40
	v_exp_f32_e32 v42, v42
	v_lshlrev_b32_e32 v51, 10, v51
	v_add_f32_e32 v42, 1.0, v42
	v_rcp_f32_e32 v42, v42
	s_nop 0
	v_mul_f32_e32 v40, v40, v42
	v_mul_f32_e32 v42, 0xbfb8aa3b, v41
	v_exp_f32_e32 v42, v42
	s_nop 0
	v_add_f32_e32 v42, 1.0, v42
	v_rcp_f32_e32 v42, v42
	s_nop 0
	v_mul_f32_e32 v41, v41, v42
	v_cvt_pk_bf16_f32 v40, v40, v41
	v_mul_f32_e32 v41, 0xbfb8aa3b, v52
	v_mul_f32_e32 v42, 0xbfb8aa3b, v53
	v_exp_f32_e32 v41, v41
	v_exp_f32_e32 v42, v42
	v_add_f32_e32 v41, 1.0, v41
	v_add_f32_e32 v42, 1.0, v42
	v_rcp_f32_e32 v41, v41
	v_rcp_f32_e32 v42, v42
	v_mul_f32_e32 v41, v52, v41
	v_mul_f32_e32 v42, v53, v42
	v_cvt_pk_bf16_f32 v41, v41, v42
	v_ashrrev_i32_e32 v42, 5, v50
	v_and_b32_e32 v42, -4, v42
	v_add_u32_e32 v42, v42, v219
	v_ashrrev_i32_e32 v43, 31, v42
	v_lshlrev_b32_e32 v52, 6, v50
	v_lshlrev_b32_e32 v53, 2, v50
	v_and_or_b32 v52, v52, s78, v221
	v_and_b32_e32 v53, 32, v53
	v_lshlrev_b64 v[42:43], 14, v[42:43]
	v_bitop3_b32 v144, v52, v51, v53 bitop3:0xde
	v_lshl_add_u64 v[42:43], s[64:65], 0, v[42:43]
	v_lshl_add_u64 v[42:43], v[42:43], 0, v[144:145]
	global_store_dwordx2 v[42:43], v[40:41], off
	v_pk_mov_b32 v[40:41], v[38:39], v[36:37] op_sel:[1,0]
	v_mov_b32_e32 v42, v38
	v_mov_b32_e32 v43, v37
	v_pk_add_f32 v[40:41], v[40:41], v[42:43]
	s_nop 0
	v_add_f32_e32 v40, v40, v41
	s_nop 1
	v_add_f32_dpp v40, v40, v40 quad_perm:[1,0,3,2] row_mask:0xf bank_mask:0xf
	s_nop 1
	v_add_f32_dpp v40, v40, v40 quad_perm:[2,3,0,1] row_mask:0xf bank_mask:0xf
	s_nop 1
	v_add_f32_dpp v40, v40, v40 row_half_mirror row_mask:0xf bank_mask:0xf
	s_nop 1
	v_add_f32_dpp v40, v40, v40 row_mirror row_mask:0xf bank_mask:0xf
	ds_bpermute_b32 v41, v48, v40
	s_waitcnt lgkmcnt(0)
	v_add_f32_e32 v40, v40, v41
	ds_bpermute_b32 v41, v49, v40
	s_waitcnt lgkmcnt(0)
; __device__ __forceinline__ unsigned cvtpk(float lo, float hi) { unsigned r; asm("v_cvt_pk_bf16_f32 %0, %1, %2" : "=v"(r) : "v"(lo), "v"(hi)); return r; }
; __device__ __forceinline__ float sigm(float x) { return __builtin_amdgcn_rcpf(1.f + __expf(-x)); }
; __device__ __forceinline__ size_t oimg(int n, int row, int c) { return (size_t)((n * (MT / 128) + (row >> 7)) * 4 + (c >> 6)) * 8192 + (size_t)(pg8::lds_byte(row & 127, c & 63) >> 1); }
; __device__ __forceinline__ float wave_sum(float v) {
; #pragma unroll
;     for (int o = 1; o < 64; o <<= 1) v += __shfl_xor(v, o);
;     return v;
; }
; __device__ __forceinline__ void phase_branch(const KP2& p, int l, LAS unsigned char* lds) {
;     ...
;                     for (int t = 0; t < 8; ++t) {
;                         f32x4 v = acc[t]; const float mu = wave_sum((v.x + v.y) + (v.z + v.w)) * (1.f / BW);
;                         v = v - mu; const float rs = rsqrtf(wave_sum((v.x * v.x + v.y * v.y) + (v.z * v.z + v.w * v.w)) * (1.f / BW) + EPS);
;                         v = v * rs * lg + lb;
;                         u32x2 w; w.x = cvtpk(v.x * sigm(v.x), v.y * sigm(v.y)); w.y = cvtpk(v.z * sigm(v.z), v.w * sigm(v.w));
;                         *(u32x2*)(O + oimg(1, row0 + tb + t, 4 * lane)) = w;
	v_add_f32_e32 v40, v40, v41
	v_fmamk_f32 v39, v40, 0xbb800000, v39
	v_fmac_f32_e32 v38, 0xbb800000, v40
	v_fmamk_f32 v37, v40, 0xbb800000, v37
	v_fmac_f32_e32 v36, 0xbb800000, v40
	v_pk_mul_f32 v[40:41], v[36:37], v[36:37]
	v_pk_mul_f32 v[42:43], v[38:39], v[38:39]
	s_nop 0
	v_pk_mov_b32 v[52:53], v[42:43], v[40:41] op_sel:[1,0]
	v_mov_b32_e32 v43, v41
	v_pk_add_f32 v[40:41], v[52:53], v[42:43]
	s_nop 0
	v_add_f32_e32 v40, v40, v41
	s_nop 1
	v_add_f32_dpp v40, v40, v40 quad_perm:[1,0,3,2] row_mask:0xf bank_mask:0xf
	s_nop 1
	v_add_f32_dpp v40, v40, v40 quad_perm:[2,3,0,1] row_mask:0xf bank_mask:0xf
	s_nop 1
	v_add_f32_dpp v40, v40, v40 row_half_mirror row_mask:0xf bank_mask:0xf
	s_nop 1
	v_add_f32_dpp v40, v40, v40 row_mirror row_mask:0xf bank_mask:0xf
	ds_bpermute_b32 v41, v48, v40
	s_waitcnt lgkmcnt(0)
	v_add_f32_e32 v40, v40, v41
	ds_bpermute_b32 v41, v49, v40
	s_waitcnt lgkmcnt(0)
	v_add_f32_e32 v40, v40, v41
	v_fmamk_f32 v40, v40, 0x3b800000, v196
	v_cmp_gt_f32_e32 vcc, s92, v40
	v_mul_f32_e32 v41, 0x4b800000, v40
	s_nop 0
	v_cndmask_b32_e32 v40, v40, v41, vcc
	v_rsq_f32_e32 v40, v40
	s_nop 0
	v_mul_f32_e32 v41, 0x45800000, v40
	v_cndmask_b32_e32 v40, v40, v41, vcc
	v_pk_mul_f32 v[38:39], v[38:39], v[40:41] op_sel_hi:[1,0]
	v_pk_mul_f32 v[36:37], v[36:37], v[40:41] op_sel_hi:[1,0]
	s_nop 0
	v_pk_fma_f32 v[40:41], v[6:7], v[36:37], v[10:11]
	v_pk_fma_f32 v[36:37], v[4:5], v[38:39], v[8:9]
	s_nop 0
	v_mul_f32_e32 v38, 0xbfb8aa3b, v36
	v_exp_f32_e32 v38, v38
	s_nop 0
	v_add_f32_e32 v38, 1.0, v38
	v_rcp_f32_e32 v38, v38
	s_nop 0
	v_mul_f32_e32 v36, v36, v38
	v_mul_f32_e32 v38, 0xbfb8aa3b, v37
	v_exp_f32_e32 v38, v38
	s_nop 0
	v_add_f32_e32 v38, 1.0, v38
	v_rcp_f32_e32 v38, v38
	s_nop 0
	v_mul_f32_e32 v37, v37, v38
	v_cvt_pk_bf16_f32 v36, v36, v37
	v_mul_f32_e32 v37, 0xbfb8aa3b, v40
	v_mul_f32_e32 v38, 0xbfb8aa3b, v41
	v_exp_f32_e32 v37, v37
	v_exp_f32_e32 v38, v38
	v_add_f32_e32 v37, 1.0, v37
	v_add_f32_e32 v38, 1.0, v38
	v_rcp_f32_e32 v37, v37
	v_rcp_f32_e32 v38, v38
	v_mul_f32_e32 v37, v40, v37
	v_mul_f32_e32 v38, v41, v38
	v_add_u32_e32 v40, 1, v50
	v_cvt_pk_bf16_f32 v37, v37, v38
	v_ashrrev_i32_e32 v38, 5, v40
	v_and_b32_e32 v38, -4, v38
	v_add_u32_e32 v38, v38, v219
	v_lshrrev_b32_e32 v41, 3, v40
	v_ashrrev_i32_e32 v39, 31, v38
	v_and_or_b32 v41, v41, 14, v220
	v_lshlrev_b32_e32 v42, 6, v40
	v_lshlrev_b32_e32 v40, 2, v40
	v_and_or_b32 v42, v42, s78, v221
	v_lshlrev_b32_e32 v41, 10, v41
	v_and_b32_e32 v40, 32, v40
	v_lshlrev_b64 v[38:39], 14, v[38:39]
	v_bitop3_b32 v144, v42, v41, v40 bitop3:0xde
	v_lshl_add_u64 v[38:39], s[64:65], 0, v[38:39]
	v_lshl_add_u64 v[38:39], v[38:39], 0, v[144:145]
	global_store_dwordx2 v[38:39], v[36:37], off
	v_pk_mov_b32 v[36:37], v[34:35], v[32:33] op_sel:[1,0]
	v_mov_b32_e32 v38, v34
	v_mov_b32_e32 v39, v33
	v_pk_add_f32 v[36:37], v[36:37], v[38:39]
	s_nop 0
	v_add_f32_e32 v36, v36, v37
	s_nop 1
	v_add_f32_dpp v36, v36, v36 quad_perm:[1,0,3,2] row_mask:0xf bank_mask:0xf
	s_nop 1
	v_add_f32_dpp v36, v36, v36 quad_perm:[2,3,0,1] row_mask:0xf bank_mask:0xf
	s_nop 1
	v_add_f32_dpp v36, v36, v36 row_half_mirror row_mask:0xf bank_mask:0xf
	s_nop 1
	v_add_f32_dpp v36, v36, v36 row_mirror row_mask:0xf bank_mask:0xf
	ds_bpermute_b32 v37, v48, v36
	s_waitcnt lgkmcnt(0)
	v_add_f32_e32 v36, v36, v37
	ds_bpermute_b32 v37, v49, v36
	s_waitcnt lgkmcnt(0)
	v_add_f32_e32 v36, v36, v37
	v_fmamk_f32 v35, v36, 0xbb800000, v35
	v_fmac_f32_e32 v34, 0xbb800000, v36
	v_fmamk_f32 v33, v36, 0xbb800000, v33
	v_fmac_f32_e32 v32, 0xbb800000, v36
	v_pk_mul_f32 v[36:37], v[32:33], v[32:33]
	v_pk_mul_f32 v[38:39], v[34:35], v[34:35]
	s_nop 0
	v_pk_mov_b32 v[40:41], v[38:39], v[36:37] op_sel:[1,0]
	v_mov_b32_e32 v39, v37
	v_pk_add_f32 v[36:37], v[40:41], v[38:39]
	s_nop 0
	v_add_f32_e32 v36, v36, v37
	s_nop 1
	v_add_f32_dpp v36, v36, v36 quad_perm:[1,0,3,2] row_mask:0xf bank_mask:0xf
	s_nop 1
	v_add_f32_dpp v36, v36, v36 quad_perm:[2,3,0,1] row_mask:0xf bank_mask:0xf
	s_nop 1
	v_add_f32_dpp v36, v36, v36 row_half_mirror row_mask:0xf bank_mask:0xf
	s_nop 1
	v_add_f32_dpp v36, v36, v36 row_mirror row_mask:0xf bank_mask:0xf
	ds_bpermute_b32 v37, v48, v36
	s_waitcnt lgkmcnt(0)
	v_add_f32_e32 v36, v36, v37
	ds_bpermute_b32 v37, v49, v36
	s_waitcnt lgkmcnt(0)
	v_add_f32_e32 v36, v36, v37
	v_fmamk_f32 v36, v36, 0x3b800000, v196
	v_cmp_gt_f32_e32 vcc, s92, v36
	v_mul_f32_e32 v37, 0x4b800000, v36
	s_nop 0
	v_cndmask_b32_e32 v36, v36, v37, vcc
	v_rsq_f32_e32 v36, v36
	s_nop 0
	v_mul_f32_e32 v37, 0x45800000, v36
	v_cndmask_b32_e32 v36, v36, v37, vcc
	v_pk_mul_f32 v[34:35], v[34:35], v[36:37] op_sel_hi:[1,0]
	v_pk_mul_f32 v[32:33], v[32:33], v[36:37] op_sel_hi:[1,0]
	v_pk_fma_f32 v[34:35], v[4:5], v[34:35], v[8:9]
	v_pk_fma_f32 v[32:33], v[6:7], v[32:33], v[10:11]
	v_mul_f32_e32 v36, 0xbfb8aa3b, v34
	v_exp_f32_e32 v36, v36
	s_nop 0
	v_add_f32_e32 v36, 1.0, v36
	v_rcp_f32_e32 v36, v36
	s_nop 0
	v_mul_f32_e32 v34, v34, v36
	v_mul_f32_e32 v36, 0xbfb8aa3b, v35
	v_exp_f32_e32 v36, v36
	s_nop 0
	v_add_f32_e32 v36, 1.0, v36
	v_rcp_f32_e32 v36, v36
	s_nop 0
	v_mul_f32_e32 v35, v35, v36
	v_cvt_pk_bf16_f32 v34, v34, v35
	v_mul_f32_e32 v35, 0xbfb8aa3b, v32
	v_exp_f32_e32 v35, v35
	v_add_u32_e32 v36, 2, v50
	v_lshrrev_b32_e32 v37, 3, v36
	v_and_or_b32 v37, v37, 14, v220
	v_add_f32_e32 v35, 1.0, v35
	v_rcp_f32_e32 v35, v35
	v_lshlrev_b32_e32 v38, 6, v36
	v_and_or_b32 v38, v38, s78, v221
	v_lshlrev_b32_e32 v37, 10, v37
	v_mul_f32_e32 v32, v32, v35
	v_mul_f32_e32 v35, 0xbfb8aa3b, v33
	v_exp_f32_e32 v35, v35
	s_nop 0
	v_add_f32_e32 v35, 1.0, v35
	v_rcp_f32_e32 v35, v35
	s_nop 0
	v_mul_f32_e32 v33, v33, v35
	v_cvt_pk_bf16_f32 v35, v32, v33
	v_ashrrev_i32_e32 v32, 5, v36
	v_and_b32_e32 v32, -4, v32
	v_add_u32_e32 v32, v32, v219
	v_ashrrev_i32_e32 v33, 31, v32
	v_lshlrev_b32_e32 v36, 2, v36
	v_and_b32_e32 v36, 32, v36
	v_lshlrev_b64 v[32:33], 14, v[32:33]
	v_bitop3_b32 v144, v38, v37, v36 bitop3:0xde
	v_lshl_add_u64 v[32:33], s[64:65], 0, v[32:33]
	v_lshl_add_u64 v[32:33], v[32:33], 0, v[144:145]
	global_store_dwordx2 v[32:33], v[34:35], off
	v_pk_mov_b32 v[32:33], v[30:31], v[28:29] op_sel:[1,0]
	v_mov_b32_e32 v34, v30
	v_mov_b32_e32 v35, v29
	v_pk_add_f32 v[32:33], v[32:33], v[34:35]
	s_nop 0
	v_add_f32_e32 v32, v32, v33
	s_nop 1
	v_add_f32_dpp v32, v32, v32 quad_perm:[1,0,3,2] row_mask:0xf bank_mask:0xf
	s_nop 1
	v_add_f32_dpp v32, v32, v32 quad_perm:[2,3,0,1] row_mask:0xf bank_mask:0xf
	s_nop 1
	v_add_f32_dpp v32, v32, v32 row_half_mirror row_mask:0xf bank_mask:0xf
	s_nop 1
	v_add_f32_dpp v32, v32, v32 row_mirror row_mask:0xf bank_mask:0xf
	ds_bpermute_b32 v33, v48, v32
	s_waitcnt lgkmcnt(0)
; __device__ __forceinline__ unsigned cvtpk(float lo, float hi) { unsigned r; asm("v_cvt_pk_bf16_f32 %0, %1, %2" : "=v"(r) : "v"(lo), "v"(hi)); return r; }
; __device__ __forceinline__ float sigm(float x) { return __builtin_amdgcn_rcpf(1.f + __expf(-x)); }
; __device__ __forceinline__ size_t oimg(int n, int row, int c) { return (size_t)((n * (MT / 128) + (row >> 7)) * 4 + (c >> 6)) * 8192 + (size_t)(pg8::lds_byte(row & 127, c & 63) >> 1); }
; __device__ __forceinline__ float wave_sum(float v) {
; #pragma unroll
;     for (int o = 1; o < 64; o <<= 1) v += __shfl_xor(v, o);
;     return v;
; }
; __device__ __forceinline__ void phase_branch(const KP2& p, int l, LAS unsigned char* lds) {
;     ...
;                     for (int t = 0; t < 8; ++t) {
;                         f32x4 v = acc[t]; const float mu = wave_sum((v.x + v.y) + (v.z + v.w)) * (1.f / BW);
;                         v = v - mu; const float rs = rsqrtf(wave_sum((v.x * v.x + v.y * v.y) + (v.z * v.z + v.w * v.w)) * (1.f / BW) + EPS);
;                         v = v * rs * lg + lb;
;                         u32x2 w; w.x = cvtpk(v.x * sigm(v.x), v.y * sigm(v.y)); w.y = cvtpk(v.z * sigm(v.z), v.w * sigm(v.w));
;                         *(u32x2*)(O + oimg(1, row0 + tb + t, 4 * lane)) = w;
;                     }
	v_add_f32_e32 v32, v32, v33
	ds_bpermute_b32 v33, v49, v32
	s_waitcnt lgkmcnt(0)
	v_add_f32_e32 v32, v32, v33
	v_fmamk_f32 v31, v32, 0xbb800000, v31
	v_fmac_f32_e32 v30, 0xbb800000, v32
	v_fmamk_f32 v29, v32, 0xbb800000, v29
	v_fmac_f32_e32 v28, 0xbb800000, v32
	v_pk_mul_f32 v[32:33], v[28:29], v[28:29]
	v_pk_mul_f32 v[34:35], v[30:31], v[30:31]
	s_nop 0
	v_pk_mov_b32 v[36:37], v[34:35], v[32:33] op_sel:[1,0]
	v_mov_b32_e32 v35, v33
	v_pk_add_f32 v[32:33], v[36:37], v[34:35]
	s_nop 0
	v_add_f32_e32 v32, v32, v33
	s_nop 1
	v_add_f32_dpp v32, v32, v32 quad_perm:[1,0,3,2] row_mask:0xf bank_mask:0xf
	s_nop 1
	v_add_f32_dpp v32, v32, v32 quad_perm:[2,3,0,1] row_mask:0xf bank_mask:0xf
	s_nop 1
	v_add_f32_dpp v32, v32, v32 row_half_mirror row_mask:0xf bank_mask:0xf
	s_nop 1
	v_add_f32_dpp v32, v32, v32 row_mirror row_mask:0xf bank_mask:0xf
	ds_bpermute_b32 v33, v48, v32
	s_waitcnt lgkmcnt(0)
	v_add_f32_e32 v32, v32, v33
	ds_bpermute_b32 v33, v49, v32
	s_waitcnt lgkmcnt(0)
	v_add_f32_e32 v32, v32, v33
	v_fmamk_f32 v32, v32, 0x3b800000, v196
	v_cmp_gt_f32_e32 vcc, s92, v32
	v_mul_f32_e32 v33, 0x4b800000, v32
	s_nop 0
	v_cndmask_b32_e32 v32, v32, v33, vcc
	v_rsq_f32_e32 v32, v32
	s_nop 0
	v_mul_f32_e32 v33, 0x45800000, v32
	v_cndmask_b32_e32 v32, v32, v33, vcc
	v_pk_mul_f32 v[30:31], v[30:31], v[32:33] op_sel_hi:[1,0]
	v_pk_mul_f32 v[28:29], v[28:29], v[32:33] op_sel_hi:[1,0]
	v_pk_fma_f32 v[30:31], v[4:5], v[30:31], v[8:9]
	v_pk_fma_f32 v[28:29], v[6:7], v[28:29], v[10:11]
	v_mul_f32_e32 v32, 0xbfb8aa3b, v30
	v_exp_f32_e32 v32, v32
	s_nop 0
	v_add_f32_e32 v32, 1.0, v32
	v_rcp_f32_e32 v32, v32
	s_nop 0
	v_mul_f32_e32 v30, v30, v32
	v_mul_f32_e32 v32, 0xbfb8aa3b, v31
	v_exp_f32_e32 v32, v32
	s_nop 0
	v_add_f32_e32 v32, 1.0, v32
	v_rcp_f32_e32 v32, v32
	s_nop 0
	v_mul_f32_e32 v31, v31, v32
	v_cvt_pk_bf16_f32 v30, v30, v31
	v_mul_f32_e32 v31, 0xbfb8aa3b, v28
	v_exp_f32_e32 v31, v31
	v_add_u32_e32 v32, 3, v50
	v_lshrrev_b32_e32 v33, 3, v32
	v_and_or_b32 v33, v33, 14, v220
	v_add_f32_e32 v31, 1.0, v31
	v_rcp_f32_e32 v31, v31
	v_lshlrev_b32_e32 v34, 6, v32
	v_and_or_b32 v34, v34, s78, v221
	v_lshlrev_b32_e32 v33, 10, v33
	v_mul_f32_e32 v28, v28, v31
	v_mul_f32_e32 v31, 0xbfb8aa3b, v29
	v_exp_f32_e32 v31, v31
	s_nop 0
	v_add_f32_e32 v31, 1.0, v31
	v_rcp_f32_e32 v31, v31
	s_nop 0
	v_mul_f32_e32 v29, v29, v31
	v_cvt_pk_bf16_f32 v31, v28, v29
	v_ashrrev_i32_e32 v28, 5, v32
	v_and_b32_e32 v28, -4, v28
	v_add_u32_e32 v28, v28, v219
	v_ashrrev_i32_e32 v29, 31, v28
	v_lshlrev_b32_e32 v32, 2, v32
	v_and_b32_e32 v32, 32, v32
	v_lshlrev_b64 v[28:29], 14, v[28:29]
	v_bitop3_b32 v144, v34, v33, v32 bitop3:0xde
	v_lshl_add_u64 v[28:29], s[64:65], 0, v[28:29]
	v_lshl_add_u64 v[28:29], v[28:29], 0, v[144:145]
	global_store_dwordx2 v[28:29], v[30:31], off
	v_pk_mov_b32 v[28:29], v[26:27], v[24:25] op_sel:[1,0]
	v_mov_b32_e32 v30, v26
	v_mov_b32_e32 v31, v25
	v_pk_add_f32 v[28:29], v[28:29], v[30:31]
	s_nop 0
	v_add_f32_e32 v28, v28, v29
	s_nop 1
	v_add_f32_dpp v28, v28, v28 quad_perm:[1,0,3,2] row_mask:0xf bank_mask:0xf
	s_nop 1
	v_add_f32_dpp v28, v28, v28 quad_perm:[2,3,0,1] row_mask:0xf bank_mask:0xf
	s_nop 1
	v_add_f32_dpp v28, v28, v28 row_half_mirror row_mask:0xf bank_mask:0xf
	s_nop 1
	v_add_f32_dpp v28, v28, v28 row_mirror row_mask:0xf bank_mask:0xf
	ds_bpermute_b32 v29, v48, v28
	s_waitcnt lgkmcnt(0)
	v_add_f32_e32 v28, v28, v29
	ds_bpermute_b32 v29, v49, v28
	s_waitcnt lgkmcnt(0)
	v_add_f32_e32 v28, v28, v29
	v_fmamk_f32 v27, v28, 0xbb800000, v27
	v_fmac_f32_e32 v26, 0xbb800000, v28
	v_fmamk_f32 v25, v28, 0xbb800000, v25
	v_fmac_f32_e32 v24, 0xbb800000, v28
	v_pk_mul_f32 v[28:29], v[24:25], v[24:25]
	v_pk_mul_f32 v[30:31], v[26:27], v[26:27]
	s_nop 0
	v_pk_mov_b32 v[32:33], v[30:31], v[28:29] op_sel:[1,0]
	v_mov_b32_e32 v31, v29
	v_pk_add_f32 v[28:29], v[32:33], v[30:31]
	s_nop 0
	v_add_f32_e32 v28, v28, v29
	s_nop 1
	v_add_f32_dpp v28, v28, v28 quad_perm:[1,0,3,2] row_mask:0xf bank_mask:0xf
	s_nop 1
	v_add_f32_dpp v28, v28, v28 quad_perm:[2,3,0,1] row_mask:0xf bank_mask:0xf
	s_nop 1
	v_add_f32_dpp v28, v28, v28 row_half_mirror row_mask:0xf bank_mask:0xf
	s_nop 1
	v_add_f32_dpp v28, v28, v28 row_mirror row_mask:0xf bank_mask:0xf
	ds_bpermute_b32 v29, v48, v28
	s_waitcnt lgkmcnt(0)
	v_add_f32_e32 v28, v28, v29
	ds_bpermute_b32 v29, v49, v28
	s_waitcnt lgkmcnt(0)
	v_add_f32_e32 v28, v28, v29
	v_fmamk_f32 v28, v28, 0x3b800000, v196
	v_cmp_gt_f32_e32 vcc, s92, v28
	v_mul_f32_e32 v29, 0x4b800000, v28
	s_nop 0
	v_cndmask_b32_e32 v28, v28, v29, vcc
	v_rsq_f32_e32 v28, v28
	s_nop 0
	v_mul_f32_e32 v29, 0x45800000, v28
	v_cndmask_b32_e32 v28, v28, v29, vcc
	v_pk_mul_f32 v[26:27], v[26:27], v[28:29] op_sel_hi:[1,0]
	v_pk_mul_f32 v[24:25], v[24:25], v[28:29] op_sel_hi:[1,0]
	v_pk_fma_f32 v[26:27], v[4:5], v[26:27], v[8:9]
	v_pk_fma_f32 v[24:25], v[6:7], v[24:25], v[10:11]
	v_mul_f32_e32 v28, 0xbfb8aa3b, v26
	v_exp_f32_e32 v28, v28
	s_nop 0
	v_add_f32_e32 v28, 1.0, v28
	v_rcp_f32_e32 v28, v28
	s_nop 0
	v_mul_f32_e32 v26, v26, v28
	v_mul_f32_e32 v28, 0xbfb8aa3b, v27
	v_exp_f32_e32 v28, v28
	s_nop 0
	v_add_f32_e32 v28, 1.0, v28
	v_rcp_f32_e32 v28, v28
	s_nop 0
	v_mul_f32_e32 v27, v27, v28
	v_cvt_pk_bf16_f32 v26, v26, v27
	v_mul_f32_e32 v27, 0xbfb8aa3b, v24
	v_exp_f32_e32 v27, v27
	v_add_u32_e32 v28, 4, v50
	v_lshrrev_b32_e32 v29, 3, v28
	v_and_or_b32 v29, v29, 14, v220
	v_add_f32_e32 v27, 1.0, v27
	v_rcp_f32_e32 v27, v27
	v_lshlrev_b32_e32 v30, 6, v28
	v_and_or_b32 v30, v30, s78, v221
	v_lshlrev_b32_e32 v29, 10, v29
	v_mul_f32_e32 v24, v24, v27
	v_mul_f32_e32 v27, 0xbfb8aa3b, v25
	v_exp_f32_e32 v27, v27
	s_nop 0
	v_add_f32_e32 v27, 1.0, v27
	v_rcp_f32_e32 v27, v27
	s_nop 0
	v_mul_f32_e32 v25, v25, v27
	v_cvt_pk_bf16_f32 v27, v24, v25
	v_ashrrev_i32_e32 v24, 5, v28
	v_and_b32_e32 v24, -4, v24
	v_add_u32_e32 v24, v24, v219
	v_ashrrev_i32_e32 v25, 31, v24
	v_lshlrev_b32_e32 v28, 2, v28
	v_and_b32_e32 v28, 32, v28
	v_lshlrev_b64 v[24:25], 14, v[24:25]
	v_bitop3_b32 v144, v30, v29, v28 bitop3:0xde
	v_lshl_add_u64 v[24:25], s[64:65], 0, v[24:25]
	v_lshl_add_u64 v[24:25], v[24:25], 0, v[144:145]
	global_store_dwordx2 v[24:25], v[26:27], off
	v_pk_mov_b32 v[24:25], v[22:23], v[20:21] op_sel:[1,0]
	v_mov_b32_e32 v26, v22
	v_mov_b32_e32 v27, v21
	v_pk_add_f32 v[24:25], v[24:25], v[26:27]
	s_nop 0
	v_add_f32_e32 v24, v24, v25
	s_nop 1
	v_add_f32_dpp v24, v24, v24 quad_perm:[1,0,3,2] row_mask:0xf bank_mask:0xf
	s_nop 1
	v_add_f32_dpp v24, v24, v24 quad_perm:[2,3,0,1] row_mask:0xf bank_mask:0xf
	s_nop 1
	v_add_f32_dpp v24, v24, v24 row_half_mirror row_mask:0xf bank_mask:0xf
	s_nop 1
	v_add_f32_dpp v24, v24, v24 row_mirror row_mask:0xf bank_mask:0xf
	ds_bpermute_b32 v25, v48, v24
	s_waitcnt lgkmcnt(0)
; __device__ __forceinline__ unsigned cvtpk(float lo, float hi) { unsigned r; asm("v_cvt_pk_bf16_f32 %0, %1, %2" : "=v"(r) : "v"(lo), "v"(hi)); return r; }
; __device__ __forceinline__ float sigm(float x) { return __builtin_amdgcn_rcpf(1.f + __expf(-x)); }
; __device__ __forceinline__ size_t oimg(int n, int row, int c) { return (size_t)((n * (MT / 128) + (row >> 7)) * 4 + (c >> 6)) * 8192 + (size_t)(pg8::lds_byte(row & 127, c & 63) >> 1); }
; __device__ __forceinline__ float wave_sum(float v) {
; #pragma unroll
;     for (int o = 1; o < 64; o <<= 1) v += __shfl_xor(v, o);
;     return v;
; }
; __device__ __forceinline__ void phase_branch(const KP2& p, int l, LAS unsigned char* lds) {
;     ...
;                     for (int t = 0; t < 8; ++t) {
;                         f32x4 v = acc[t]; const float mu = wave_sum((v.x + v.y) + (v.z + v.w)) * (1.f / BW);
;                         v = v - mu; const float rs = rsqrtf(wave_sum((v.x * v.x + v.y * v.y) + (v.z * v.z + v.w * v.w)) * (1.f / BW) + EPS);
;                         v = v * rs * lg + lb;
;                         u32x2 w; w.x = cvtpk(v.x * sigm(v.x), v.y * sigm(v.y)); w.y = cvtpk(v.z * sigm(v.z), v.w * sigm(v.w));
;                         *(u32x2*)(O + oimg(1, row0 + tb + t, 4 * lane)) = w;
;                     }
	v_add_f32_e32 v24, v24, v25
	ds_bpermute_b32 v25, v49, v24
	s_waitcnt lgkmcnt(0)
	v_add_f32_e32 v24, v24, v25
	v_fmamk_f32 v23, v24, 0xbb800000, v23
	v_fmac_f32_e32 v22, 0xbb800000, v24
	v_fmamk_f32 v21, v24, 0xbb800000, v21
	v_fmac_f32_e32 v20, 0xbb800000, v24
	v_pk_mul_f32 v[24:25], v[20:21], v[20:21]
	v_pk_mul_f32 v[26:27], v[22:23], v[22:23]
	s_nop 0
	v_pk_mov_b32 v[28:29], v[26:27], v[24:25] op_sel:[1,0]
	v_mov_b32_e32 v27, v25
	v_pk_add_f32 v[24:25], v[28:29], v[26:27]
	s_nop 0
	v_add_f32_e32 v24, v24, v25
	s_nop 1
	v_add_f32_dpp v24, v24, v24 quad_perm:[1,0,3,2] row_mask:0xf bank_mask:0xf
	s_nop 1
	v_add_f32_dpp v24, v24, v24 quad_perm:[2,3,0,1] row_mask:0xf bank_mask:0xf
	s_nop 1
	v_add_f32_dpp v24, v24, v24 row_half_mirror row_mask:0xf bank_mask:0xf
	s_nop 1
	v_add_f32_dpp v24, v24, v24 row_mirror row_mask:0xf bank_mask:0xf
	ds_bpermute_b32 v25, v48, v24
	s_waitcnt lgkmcnt(0)
	v_add_f32_e32 v24, v24, v25
	ds_bpermute_b32 v25, v49, v24
	s_waitcnt lgkmcnt(0)
	v_add_f32_e32 v24, v24, v25
	v_fmamk_f32 v24, v24, 0x3b800000, v196
	v_cmp_gt_f32_e32 vcc, s92, v24
	v_mul_f32_e32 v25, 0x4b800000, v24
	s_nop 0
	v_cndmask_b32_e32 v24, v24, v25, vcc
	v_rsq_f32_e32 v24, v24
	s_nop 0
	v_mul_f32_e32 v25, 0x45800000, v24
	v_cndmask_b32_e32 v24, v24, v25, vcc
	v_pk_mul_f32 v[22:23], v[22:23], v[24:25] op_sel_hi:[1,0]
	v_pk_mul_f32 v[20:21], v[20:21], v[24:25] op_sel_hi:[1,0]
	s_nop 0
	v_pk_fma_f32 v[24:25], v[6:7], v[20:21], v[10:11]
	v_pk_fma_f32 v[20:21], v[4:5], v[22:23], v[8:9]
	s_nop 0
	v_mul_f32_e32 v22, 0xbfb8aa3b, v20
	v_exp_f32_e32 v22, v22
	s_nop 0
	v_add_f32_e32 v22, 1.0, v22
	v_rcp_f32_e32 v22, v22
	s_nop 0
	v_mul_f32_e32 v20, v20, v22
	v_mul_f32_e32 v22, 0xbfb8aa3b, v21
	v_exp_f32_e32 v22, v22
	s_nop 0
	v_add_f32_e32 v22, 1.0, v22
	v_rcp_f32_e32 v22, v22
	s_nop 0
	v_mul_f32_e32 v21, v21, v22
	v_cvt_pk_bf16_f32 v20, v20, v21
	v_mul_f32_e32 v21, 0xbfb8aa3b, v24
	v_mul_f32_e32 v22, 0xbfb8aa3b, v25
	v_exp_f32_e32 v21, v21
	v_exp_f32_e32 v22, v22
	v_add_f32_e32 v21, 1.0, v21
	v_add_f32_e32 v22, 1.0, v22
	v_rcp_f32_e32 v21, v21
	v_rcp_f32_e32 v22, v22
	v_mul_f32_e32 v21, v24, v21
	v_mul_f32_e32 v22, v25, v22
	v_add_u32_e32 v24, 5, v50
	v_cvt_pk_bf16_f32 v21, v21, v22
	v_ashrrev_i32_e32 v22, 5, v24
	v_and_b32_e32 v22, -4, v22
	v_add_u32_e32 v22, v22, v219
	v_lshrrev_b32_e32 v25, 3, v24
	v_ashrrev_i32_e32 v23, 31, v22
	v_and_or_b32 v25, v25, 14, v220
	v_lshlrev_b32_e32 v26, 6, v24
	v_lshlrev_b32_e32 v24, 2, v24
	v_and_or_b32 v26, v26, s78, v221
	v_lshlrev_b32_e32 v25, 10, v25
	v_and_b32_e32 v24, 32, v24
	v_lshlrev_b64 v[22:23], 14, v[22:23]
	v_bitop3_b32 v144, v26, v25, v24 bitop3:0xde
	v_lshl_add_u64 v[22:23], s[64:65], 0, v[22:23]
	v_lshl_add_u64 v[22:23], v[22:23], 0, v[144:145]
	global_store_dwordx2 v[22:23], v[20:21], off
	v_pk_mov_b32 v[20:21], v[18:19], v[16:17] op_sel:[1,0]
	v_mov_b32_e32 v22, v18
	v_mov_b32_e32 v23, v17
	v_pk_add_f32 v[20:21], v[20:21], v[22:23]
	s_nop 0
	v_add_f32_e32 v20, v20, v21
	s_nop 1
	v_add_f32_dpp v20, v20, v20 quad_perm:[1,0,3,2] row_mask:0xf bank_mask:0xf
	s_nop 1
	v_add_f32_dpp v20, v20, v20 quad_perm:[2,3,0,1] row_mask:0xf bank_mask:0xf
	s_nop 1
	v_add_f32_dpp v20, v20, v20 row_half_mirror row_mask:0xf bank_mask:0xf
	s_nop 1
	v_add_f32_dpp v20, v20, v20 row_mirror row_mask:0xf bank_mask:0xf
	ds_bpermute_b32 v21, v48, v20
	s_waitcnt lgkmcnt(0)
	v_add_f32_e32 v20, v20, v21
	ds_bpermute_b32 v21, v49, v20
	s_waitcnt lgkmcnt(0)
	v_add_f32_e32 v20, v20, v21
	v_fmamk_f32 v19, v20, 0xbb800000, v19
	v_fmac_f32_e32 v18, 0xbb800000, v20
	v_fmamk_f32 v17, v20, 0xbb800000, v17
	v_fmac_f32_e32 v16, 0xbb800000, v20
	v_pk_mul_f32 v[20:21], v[16:17], v[16:17]
	v_pk_mul_f32 v[22:23], v[18:19], v[18:19]
	s_nop 0
	v_pk_mov_b32 v[24:25], v[22:23], v[20:21] op_sel:[1,0]
	v_mov_b32_e32 v23, v21
	v_pk_add_f32 v[20:21], v[24:25], v[22:23]
	s_nop 0
	v_add_f32_e32 v20, v20, v21
	s_nop 1
	v_add_f32_dpp v20, v20, v20 quad_perm:[1,0,3,2] row_mask:0xf bank_mask:0xf
	s_nop 1
	v_add_f32_dpp v20, v20, v20 quad_perm:[2,3,0,1] row_mask:0xf bank_mask:0xf
	s_nop 1
	v_add_f32_dpp v20, v20, v20 row_half_mirror row_mask:0xf bank_mask:0xf
	s_nop 1
	v_add_f32_dpp v20, v20, v20 row_mirror row_mask:0xf bank_mask:0xf
	ds_bpermute_b32 v21, v48, v20
	s_waitcnt lgkmcnt(0)
	v_add_f32_e32 v20, v20, v21
	ds_bpermute_b32 v21, v49, v20
	s_waitcnt lgkmcnt(0)
; __device__ __forceinline__ unsigned cvtpk(float lo, float hi) { unsigned r; asm("v_cvt_pk_bf16_f32 %0, %1, %2" : "=v"(r) : "v"(lo), "v"(hi)); return r; }
; __device__ __forceinline__ float sigm(float x) { return __builtin_amdgcn_rcpf(1.f + __expf(-x)); }
; __device__ __forceinline__ size_t oimg(int n, int row, int c) { return (size_t)((n * (MT / 128) + (row >> 7)) * 4 + (c >> 6)) * 8192 + (size_t)(pg8::lds_byte(row & 127, c & 63) >> 1); }
; __device__ __forceinline__ void phase_branch(const KP2& p, int l, LAS unsigned char* lds) {
;     ...
;                 for (int grp = 0; grp < 2; ++grp) {
;                     const int tb = i0 + grp * 8;
;     ...
;                     for (int t = 0; t < 8; ++t) {
;                         f32x4 v = acc[t]; const float mu = wave_sum((v.x + v.y) + (v.z + v.w)) * (1.f / BW);
;                         v = v - mu; const float rs = rsqrtf(wave_sum((v.x * v.x + v.y * v.y) + (v.z * v.z + v.w * v.w)) * (1.f / BW) + EPS);
;                         v = v * rs * lg + lb;
;                         u32x2 w; w.x = cvtpk(v.x * sigm(v.x), v.y * sigm(v.y)); w.y = cvtpk(v.z * sigm(v.z), v.w * sigm(v.w));
;                         *(u32x2*)(O + oimg(1, row0 + tb + t, 4 * lane)) = w;
;                     }
	v_add_f32_e32 v20, v20, v21
	v_fmamk_f32 v20, v20, 0x3b800000, v196
	v_cmp_gt_f32_e32 vcc, s92, v20
	v_mul_f32_e32 v21, 0x4b800000, v20
	s_nop 0
	v_cndmask_b32_e32 v20, v20, v21, vcc
	v_rsq_f32_e32 v20, v20
	s_nop 0
	v_mul_f32_e32 v21, 0x45800000, v20
	v_cndmask_b32_e32 v20, v20, v21, vcc
	v_pk_mul_f32 v[18:19], v[18:19], v[20:21] op_sel_hi:[1,0]
	v_pk_mul_f32 v[16:17], v[16:17], v[20:21] op_sel_hi:[1,0]
	v_pk_fma_f32 v[18:19], v[4:5], v[18:19], v[8:9]
	v_pk_fma_f32 v[16:17], v[6:7], v[16:17], v[10:11]
	v_mul_f32_e32 v20, 0xbfb8aa3b, v18
	v_exp_f32_e32 v20, v20
	s_nop 0
	v_add_f32_e32 v20, 1.0, v20
	v_rcp_f32_e32 v20, v20
	s_nop 0
	v_mul_f32_e32 v18, v18, v20
	v_mul_f32_e32 v20, 0xbfb8aa3b, v19
	v_exp_f32_e32 v20, v20
	s_nop 0
	v_add_f32_e32 v20, 1.0, v20
	v_rcp_f32_e32 v20, v20
	s_nop 0
	v_mul_f32_e32 v19, v19, v20
	v_cvt_pk_bf16_f32 v18, v18, v19
	v_mul_f32_e32 v19, 0xbfb8aa3b, v16
	v_exp_f32_e32 v19, v19
	v_add_u32_e32 v20, 6, v50
	v_lshrrev_b32_e32 v21, 3, v20
	v_and_or_b32 v21, v21, 14, v220
	v_add_f32_e32 v19, 1.0, v19
	v_rcp_f32_e32 v19, v19
	v_lshlrev_b32_e32 v22, 6, v20
	v_and_or_b32 v22, v22, s78, v221
	v_lshlrev_b32_e32 v21, 10, v21
	v_mul_f32_e32 v16, v16, v19
	v_mul_f32_e32 v19, 0xbfb8aa3b, v17
	v_exp_f32_e32 v19, v19
	s_nop 0
	v_add_f32_e32 v19, 1.0, v19
	v_rcp_f32_e32 v19, v19
	s_nop 0
	v_mul_f32_e32 v17, v17, v19
	v_cvt_pk_bf16_f32 v19, v16, v17
	v_ashrrev_i32_e32 v16, 5, v20
	v_and_b32_e32 v16, -4, v16
	v_add_u32_e32 v16, v16, v219
	v_ashrrev_i32_e32 v17, 31, v16
	v_lshlrev_b32_e32 v20, 2, v20
	v_and_b32_e32 v20, 32, v20
	v_lshlrev_b64 v[16:17], 14, v[16:17]
	v_bitop3_b32 v144, v22, v21, v20 bitop3:0xde
	v_lshl_add_u64 v[16:17], s[64:65], 0, v[16:17]
	v_lshl_add_u64 v[16:17], v[16:17], 0, v[144:145]
	global_store_dwordx2 v[16:17], v[18:19], off
	v_pk_mov_b32 v[16:17], v[14:15], v[12:13] op_sel:[1,0]
	v_mov_b32_e32 v18, v14
	v_mov_b32_e32 v19, v13
	v_pk_add_f32 v[16:17], v[16:17], v[18:19]
	s_nop 0
	v_add_f32_e32 v16, v16, v17
	s_nop 1
	v_add_f32_dpp v16, v16, v16 quad_perm:[1,0,3,2] row_mask:0xf bank_mask:0xf
	s_nop 1
	v_add_f32_dpp v16, v16, v16 quad_perm:[2,3,0,1] row_mask:0xf bank_mask:0xf
	s_nop 1
	v_add_f32_dpp v16, v16, v16 row_half_mirror row_mask:0xf bank_mask:0xf
	s_nop 1
	v_add_f32_dpp v16, v16, v16 row_mirror row_mask:0xf bank_mask:0xf
	ds_bpermute_b32 v17, v48, v16
	s_waitcnt lgkmcnt(0)
	v_add_f32_e32 v16, v16, v17
	ds_bpermute_b32 v17, v49, v16
	s_waitcnt lgkmcnt(0)
	v_add_f32_e32 v16, v16, v17
	v_fmamk_f32 v15, v16, 0xbb800000, v15
	v_fmac_f32_e32 v14, 0xbb800000, v16
	v_fmamk_f32 v13, v16, 0xbb800000, v13
	v_fmac_f32_e32 v12, 0xbb800000, v16
	v_pk_mul_f32 v[16:17], v[12:13], v[12:13]
	v_pk_mul_f32 v[18:19], v[14:15], v[14:15]
	s_nop 0
	v_pk_mov_b32 v[20:21], v[18:19], v[16:17] op_sel:[1,0]
	v_mov_b32_e32 v19, v17
	v_pk_add_f32 v[16:17], v[20:21], v[18:19]
	s_nop 0
	v_add_f32_e32 v16, v16, v17
	s_nop 1
	v_add_f32_dpp v16, v16, v16 quad_perm:[1,0,3,2] row_mask:0xf bank_mask:0xf
	s_nop 1
	v_add_f32_dpp v16, v16, v16 quad_perm:[2,3,0,1] row_mask:0xf bank_mask:0xf
	s_nop 1
	v_add_f32_dpp v16, v16, v16 row_half_mirror row_mask:0xf bank_mask:0xf
	s_nop 1
	v_add_f32_dpp v16, v16, v16 row_mirror row_mask:0xf bank_mask:0xf
	ds_bpermute_b32 v17, v48, v16
	s_waitcnt lgkmcnt(0)
	v_add_f32_e32 v16, v16, v17
	ds_bpermute_b32 v17, v49, v16
	s_waitcnt lgkmcnt(0)
	v_add_f32_e32 v16, v16, v17
	v_fmamk_f32 v16, v16, 0x3b800000, v196
	v_cmp_gt_f32_e32 vcc, s92, v16
	v_mul_f32_e32 v17, 0x4b800000, v16
	s_nop 0
	v_cndmask_b32_e32 v16, v16, v17, vcc
	v_rsq_f32_e32 v16, v16
	s_nop 0
	v_mul_f32_e32 v17, 0x45800000, v16
	v_cndmask_b32_e32 v16, v16, v17, vcc
	v_pk_mul_f32 v[14:15], v[14:15], v[16:17] op_sel_hi:[1,0]
	v_pk_mul_f32 v[12:13], v[12:13], v[16:17] op_sel_hi:[1,0]
	v_pk_fma_f32 v[14:15], v[4:5], v[14:15], v[8:9]
	v_pk_fma_f32 v[12:13], v[6:7], v[12:13], v[10:11]
	v_mul_f32_e32 v16, 0xbfb8aa3b, v14
	v_exp_f32_e32 v16, v16
	s_and_b64 vcc, exec, s[12:13]
	s_mov_b64 s[12:13], 0
	v_add_f32_e32 v16, 1.0, v16
	v_rcp_f32_e32 v16, v16
	s_nop 0
	v_mul_f32_e32 v14, v14, v16
	v_mul_f32_e32 v16, 0xbfb8aa3b, v15
	v_exp_f32_e32 v16, v16
	s_nop 0
	v_add_f32_e32 v16, 1.0, v16
	v_rcp_f32_e32 v16, v16
	s_nop 0
	v_mul_f32_e32 v15, v15, v16
	v_cvt_pk_bf16_f32 v14, v14, v15
	v_mul_f32_e32 v15, 0xbfb8aa3b, v12
	v_exp_f32_e32 v15, v15
	v_add_u32_e32 v16, 7, v50
	v_lshrrev_b32_e32 v17, 3, v16
	v_and_or_b32 v17, v17, 14, v220
	v_add_f32_e32 v15, 1.0, v15
	v_rcp_f32_e32 v15, v15
	v_lshlrev_b32_e32 v18, 6, v16
	v_and_or_b32 v18, v18, s78, v221
	v_lshlrev_b32_e32 v17, 10, v17
	v_mul_f32_e32 v12, v12, v15
	v_mul_f32_e32 v15, 0xbfb8aa3b, v13
	v_exp_f32_e32 v15, v15
	s_nop 0
	v_add_f32_e32 v15, 1.0, v15
	v_rcp_f32_e32 v15, v15
	s_nop 0
	v_mul_f32_e32 v13, v13, v15
	v_cvt_pk_bf16_f32 v15, v12, v13
	v_ashrrev_i32_e32 v12, 5, v16
	v_and_b32_e32 v12, -4, v12
	v_add_u32_e32 v12, v12, v219
	v_ashrrev_i32_e32 v13, 31, v12
	v_lshlrev_b32_e32 v16, 2, v16
	v_and_b32_e32 v16, 32, v16
	v_lshlrev_b64 v[12:13], 14, v[12:13]
	v_bitop3_b32 v144, v18, v17, v16 bitop3:0xde
	v_lshl_add_u64 v[12:13], s[64:65], 0, v[12:13]
	v_lshl_add_u64 v[12:13], v[12:13], 0, v[144:145]
	global_store_dwordx2 v[12:13], v[14:15], off
	s_cbranch_vccnz .LBB0_436
